# dnpre: forward-substitution LDS reads hoisted 6 reads ahead into free VGPRs (lgkmcnt recounted), on top of batched l2norm
# speedup vs baseline: 1.2071x; 1.0029x over previous
; __device__ __forceinline__ bf16x8 pack8v(f32x4 a, f32x4 b) { return pack8(a[0], a[1], a[2], a[3], b[0], b[1], b[2], b[3]); }
; __device__ void ph_dnpre(const P& p, float* lds) {
;     ...
; #pragma unroll
;       for (int kb = 0; kb < 2; ++kb)
;         *(bf16x8*)(DNQK + (size_t)chunk * 4096 + ((w * 2 + kb) * 64 + lane) * 8) = pack8v(qk[2 * kb], qk[2 * kb + 1]);
;       {
;         const float eg = __expf(sG[w * 16 + fr]);
; #pragma unroll
;         for (int kb = 0; kb < 2; ++kb) {
;           const float4 a = *(const float4*)(B0 + (w * 16 + fr) * LS + kb * 32 + fq * 4);
;           const float4 c = *(const float4*)(B0 + (w * 16 + fr) * LS + kb * 32 + 16 + fq * 4);
;           *(bf16x8*)(DNQH + (size_t)chunk * 4096 + ((w * 2 + kb) * 64 + lane) * 8) =
;               pack8(a.x * eg, a.y * eg, a.z * eg, a.w * eg, c.x * eg, c.y * eg, c.z * eg, c.w * eg);
;         }
;       }
;       {
;         const int d = w * 16 + fr;
; #pragma unroll
;         for (int kb = 0; kb < 2; ++kb) {
;           float v[8];
; #pragma unroll
;           for (int e = 0; e < 8; ++e) {
;             int tk = kb * 32 + (e >> 2) * 16 + fq * 4 + (e & 3);
;             v[e] = B1[tk * LS + d] * __expf(glast - sG[tk]);
;           }
;           *(bf16x8*)(DNKT + (size_t)chunk * 4096 + ((w * 2 + kb) * 64 + lane) * 8) = pack8(v[0], v[1], v[2], v[3], v[4], v[5], v[6], v[7]);
;         }
;       }
;     }
;     __syncthreads();
; #pragma unroll
;     for (int mt = 0; mt < 4; ++mt)
; #pragma unroll
;       for (int r = 0; r < 4; ++r) {
;         const int j = w * 16 + fr;
;         B0[(j & 1) * 2048 + (mt * 16 + fq * 4 + r) * 32 + (j >> 1)] = kk[mt][r];
;       }
;     __syncthreads();
.LBB0_244:
	s_or_b64 exec, exec, s[10:11]
	s_ashr_i32 s3, s2, 31
	s_lshl_b64 s[56:57], s[2:3], 13
	v_lshl_add_u64 v[14:15], v[52:53], 0, s[56:57]
	v_cvt_pk_bf16_f32 v2, v24, v25
	v_cvt_pk_bf16_f32 v3, v26, v27
	v_cvt_pk_bf16_f32 v4, v4, v5
	v_cvt_pk_bf16_f32 v5, v6, v7
	global_store_dwordx4 v[14:15], v[2:5], off offset:1024
	v_mul_f32_e32 v1, 0x3fb8aa3b, v152
	ds_read_b128 v[2:5], v67
	v_exp_f32_e32 v6, v1
	v_cvt_pk_bf16_f32 v8, v16, v17
	v_cvt_pk_bf16_f32 v9, v18, v19
	v_cvt_pk_bf16_f32 v10, v20, v21
	v_cvt_pk_bf16_f32 v11, v22, v23
	global_store_dwordx4 v[14:15], v[8:11], off
	v_sub_f32_e32 v1, v44, v154
	v_mul_f32_e32 v1, 0x3fb8aa3b, v1
	s_waitcnt lgkmcnt(0)
	v_pk_mul_f32 v[8:9], v[6:7], v[2:3] op_sel_hi:[0,1]
	v_pk_mul_f32 v[10:11], v[6:7], v[4:5] op_sel_hi:[0,1]
	ds_read_b128 v[2:5], v67 offset:64
	s_movk_i32 s10, 0x400
	v_add_u32_e64 v24, s10, 0
	s_movk_i32 s10, 0x800
	s_waitcnt lgkmcnt(0)
	v_pk_mul_f32 v[14:15], v[6:7], v[2:3] op_sel_hi:[0,1]
	v_pk_mul_f32 v[16:17], v[6:7], v[4:5] op_sel_hi:[0,1]
	v_cvt_pk_bf16_f32 v2, v8, v9
	v_cvt_pk_bf16_f32 v3, v10, v11
	v_cvt_pk_bf16_f32 v4, v14, v15
	v_cvt_pk_bf16_f32 v5, v16, v17
	v_lshl_add_u64 v[8:9], v[54:55], 0, s[56:57]
	global_store_dwordx4 v[8:9], v[2:5], off
	ds_read_b128 v[2:5], v67 offset:128
	s_waitcnt lgkmcnt(0)
	v_pk_mul_f32 v[10:11], v[6:7], v[2:3] op_sel_hi:[0,1]
	v_pk_mul_f32 v[14:15], v[6:7], v[4:5] op_sel_hi:[0,1]
	ds_read_b128 v[2:5], v67 offset:192
	s_waitcnt lgkmcnt(0)
	v_pk_mul_f32 v[16:17], v[6:7], v[2:3] op_sel_hi:[0,1]
	v_pk_mul_f32 v[6:7], v[6:7], v[4:5] op_sel_hi:[0,1]
	v_cvt_pk_bf16_f32 v2, v10, v11
	v_cvt_pk_bf16_f32 v3, v14, v15
	v_cvt_pk_bf16_f32 v4, v16, v17
	v_cvt_pk_bf16_f32 v5, v6, v7
	global_store_dwordx4 v[8:9], v[2:5], off offset:1024
	ds_read_b32 v2, v71 offset:17408
	ds_read_b32 v9, v72 offset:17952
	v_exp_f32_e32 v4, v1
	v_add_u32_e32 v1, 0x4400, v72
	ds_read2_b32 v[6:7], v1 offset1:68
	v_sub_f32_e32 v1, v44, v156
	v_mul_f32_e32 v1, 0x3fb8aa3b, v1
	v_exp_f32_e32 v5, v1
	v_sub_f32_e32 v1, v44, v157
	s_waitcnt lgkmcnt(0)
	v_mov_b32_e32 v3, v6
	v_mul_f32_e32 v1, 0x3fb8aa3b, v1
	v_pk_mul_f32 v[2:3], v[4:5], v[2:3]
	v_exp_f32_e32 v4, v1
	v_sub_f32_e32 v1, v44, v159
	v_mul_f32_e32 v1, 0x3fb8aa3b, v1
	v_exp_f32_e32 v5, v1
	v_add_u32_e32 v1, 0x5200, v72
	v_mov_b32_e32 v8, v7
	ds_read2_b32 v[6:7], v1 offset0:124 offset1:192
	v_sub_f32_e32 v1, v44, v162
	v_mul_f32_e32 v1, 0x3fb8aa3b, v1
	v_pk_mul_f32 v[4:5], v[4:5], v[8:9]
	v_exp_f32_e32 v8, v1
	v_sub_f32_e32 v1, v44, v164
	v_mul_f32_e32 v1, 0x3fb8aa3b, v1
	v_exp_f32_e32 v9, v1
	v_add_u32_e32 v1, 0x5400, v72
	v_cvt_pk_bf16_f32 v2, v2, v3
	v_cvt_pk_bf16_f32 v3, v4, v5
	s_waitcnt lgkmcnt(0)
	v_pk_mul_f32 v[6:7], v[8:9], v[6:7]
	ds_read2_b32 v[8:9], v1 offset0:132 offset1:200
	v_sub_f32_e32 v1, v44, v165
	v_mul_f32_e32 v1, 0x3fb8aa3b, v1
	v_exp_f32_e32 v10, v1
	v_sub_f32_e32 v1, v44, v166
	v_mul_f32_e32 v1, 0x3fb8aa3b, v1
	v_exp_f32_e32 v11, v1
	v_cvt_pk_bf16_f32 v4, v6, v7
	v_lshl_add_u64 v[6:7], v[56:57], 0, s[56:57]
	v_add_u32_e32 v1, 0x6400, v72
	s_waitcnt lgkmcnt(0)
	v_pk_mul_f32 v[8:9], v[10:11], v[8:9]
	s_nop 0
	v_cvt_pk_bf16_f32 v5, v8, v9
	global_store_dwordx4 v[6:7], v[2:5], off
	ds_read2_b32 v[2:3], v1 offset0:60 offset1:128
	v_sub_f32_e32 v1, v44, v169
	v_mul_f32_e32 v1, 0x3fb8aa3b, v1
	v_exp_f32_e32 v4, v1
	v_sub_f32_e32 v1, v44, v170
	v_mul_f32_e32 v1, 0x3fb8aa3b, v1
	v_exp_f32_e32 v5, v1
	v_add_u32_e32 v1, 0x6600, v72
	s_waitcnt lgkmcnt(0)
	v_pk_mul_f32 v[2:3], v[4:5], v[2:3]
	ds_read2_b32 v[4:5], v1 offset0:68 offset1:136
	v_sub_f32_e32 v1, v44, v171
	v_mul_f32_e32 v1, 0x3fb8aa3b, v1
	v_exp_f32_e32 v8, v1
	v_sub_f32_e32 v1, v44, v37
	v_mul_f32_e32 v1, 0x3fb8aa3b, v1
	v_exp_f32_e32 v9, v1
	v_add_u32_e32 v1, 0x7400, v72
	v_cvt_pk_bf16_f32 v2, v2, v3
	v_add_u32_e32 v37, 0x1000, v63
	s_waitcnt lgkmcnt(0)
	v_pk_mul_f32 v[4:5], v[8:9], v[4:5]
	ds_read2_b32 v[8:9], v1 offset0:124 offset1:192
	v_sub_f32_e32 v1, v44, v30
	v_mul_f32_e32 v1, 0x3fb8aa3b, v1
	v_exp_f32_e32 v10, v1
	v_sub_f32_e32 v1, v44, v32
	v_mul_f32_e32 v1, 0x3fb8aa3b, v1
	v_exp_f32_e32 v11, v1
	v_add_u32_e32 v1, 0x7800, v72
	v_cvt_pk_bf16_f32 v3, v4, v5
	s_waitcnt lgkmcnt(0)
	v_pk_mul_f32 v[8:9], v[10:11], v[8:9]
	ds_read2_b32 v[10:11], v1 offset0:4 offset1:72
	v_sub_f32_e32 v1, v44, v33
	v_mul_f32_e32 v1, 0x3fb8aa3b, v1
	v_exp_f32_e32 v14, v1
	v_sub_f32_e32 v1, v44, v13
	v_mul_f32_e32 v1, 0x3fb8aa3b, v1
	v_exp_f32_e32 v15, v1
	v_cvt_pk_bf16_f32 v4, v8, v9
	v_mov_b32_dpp v8, v45 quad_perm:[1,0,3,2] row_mask:0xf bank_mask:0xf bound_ctrl:1
	v_add_f32_e32 v8, 0, v8
	s_waitcnt lgkmcnt(0)
	v_pk_mul_f32 v[10:11], v[14:15], v[10:11]
	s_nop 0
	v_cvt_pk_bf16_f32 v5, v10, v11
	global_store_dwordx4 v[6:7], v[2:5], off offset:1024
	s_barrier
	ds_write_b32 v73, v59
	ds_write_b32 v74, v151
	ds_write_b32 v75, v153
	ds_write_b32 v76, v155
	ds_write_b32 v77, v158
	ds_write_b32 v78, v160
	ds_write_b32 v79, v161
	ds_write_b32 v80, v163
	ds_write_b32 v81, v167
	ds_write_b32 v82, v168
	ds_write_b32 v83, v36
	ds_write_b32 v84, v28
	ds_write_b32 v85, v29
	ds_write_b32 v86, v31
	ds_write_b32 v87, v12
	ds_write_b32 v88, v0
	s_waitcnt lgkmcnt(0)
	s_barrier
; __device__ void ph_dnpre(const P& p, float* lds) {
;     ...
;     {
;       const int c = tid >> 1, par = tid & 1;
;       float xe[32];
;       float* col = c < 64 ? (B2 + c) : (B1 + c - 64);
;       const float* Lp = B0 + par * 2048;
; #pragma unroll
;       for (int i = 0; i < 64; ++i) {
;         float sc = sBeta[i];
;         if (c >= 64) sc *= sEG[i];
;         const float rhs = col[i * LS] * sc;
;         float a0 = 0.f, a1 = 0.f;
; #pragma unroll
;         for (int jj = 0; 2 * jj + 1 < i; ++jj) {
;           const float l = Lp[i * 32 + jj];
;           if (jj & 1) a1 += l * xe[jj]; else a0 += l * xe[jj];
;         }
;         if (i & 1) {
;           const float l = B0[i * 32 + (i >> 1)];
;           a0 += (par == 0) ? l * xe[i >> 1] : 0.f;
;         }
;         float acc = a0 + a1;
;         acc += dpp_f<DPP_XOR1>(acc);
;         const float xi = rhs - acc;
;         if ((i & 1) == 0) xe[i >> 1] = xi;
;         else xe[i >> 1] = (par == 1) ? xi : xe[i >> 1];
;       }
	ds_read_b128 v[0:3], v45 offset:52480
	ds_read_b128 v[4:7], v45 offset:52736
	ds_read_b32 v218, v89
	ds_read2_b32 v[186:187], v62 offset0:68 offset1:136
	ds_read2_b32 v[190:191], v45 offset0:32 offset1:97
	ds_read2_b32 v[194:195], v63 offset0:64 offset1:96
	v_add_u32_e32 v198, 0x200, v62
	ds_read2_b32 v[198:199], v198 offset0:76 offset1:144
	ds_read_b128 v[202:205], v45 offset:52496
	v_add_u32_e64 v28, s10, 0
	v_add_u32_e32 v29, 0x800, v63
	s_movk_i32 s10, 0xc00
	v_add_u32_e64 v32, s10, 0
	s_waitcnt lgkmcnt(6)
	v_mul_f32_e32 v4, v0, v4
	v_cndmask_b32_e64 v0, v0, v4, s[4:5]
	ds_read_b128 v[206:209], v45 offset:52752
	s_movk_i32 s10, 0x1000
	v_add_u32_e64 v36, s10, 0
	s_movk_i32 s10, 0x1400
	v_add_u32_e64 v59, s10, 0
	s_waitcnt lgkmcnt(6)
	v_fma_f32 v8, v218, v0, -v8
	v_mul_f32_e32 v0, v1, v5
	v_cndmask_b32_e64 v9, v1, v0, s[4:5]
	ds_read2_b64 v[210:213], v63 offset0:64 offset1:80
	ds_read2_b32 v[218:219], v45 offset0:162 offset1:227
	s_movk_i32 s10, 0x1800
	v_add_u32_e64 v151, s10, 0
	s_movk_i32 s10, 0x1c00
	s_waitcnt lgkmcnt(6)
	v_fma_f32 v4, v8, v190, 0
	v_cndmask_b32_e64 v4, 0, v4, s[6:7]
	s_nop 1
	v_add_f32_dpp v4, v4, v4 quad_perm:[1,0,3,2] row_mask:0xf bank_mask:0xf bound_ctrl:1
	v_fma_f32 v0, v186, v9, -v4
	v_cndmask_b32_e64 v14, v0, v8, s[6:7]
	v_add_u32_e32 v214, 0x400, v62
	ds_read2_b32 v[214:215], v214 offset0:84 offset1:152
	v_mul_f32_e32 v0, v2, v6
	v_cndmask_b32_e64 v0, v2, v0, s[4:5]
	s_waitcnt lgkmcnt(6)
	v_fma_f32 v2, v194, v14, 0
	s_nop 1
	v_add_f32_dpp v2, v2, v2 quad_perm:[1,0,3,2] row_mask:0xf bank_mask:0xf bound_ctrl:1
	v_fma_f32 v0, v187, v0, -v2
	v_mul_f32_e32 v1, v3, v7
	ds_read_b96 v[186:188], v63 offset:768
	v_cndmask_b32_e64 v1, v3, v1, s[4:5]
	v_mul_f32_e32 v3, v0, v191
	v_fma_f32 v2, v14, v195, 0
	v_cndmask_b32_e64 v3, 0, v3, s[6:7]
	v_add_f32_e32 v2, v2, v3
	s_nop 1
	v_add_f32_dpp v2, v2, v2 quad_perm:[1,0,3,2] row_mask:0xf bank_mask:0xf bound_ctrl:1
	s_waitcnt lgkmcnt(6)
	v_fma_f32 v1, v198, v1, -v2
	v_cndmask_b32_e64 v15, v1, v0, s[6:7]
	v_add_u32_e32 v190, 0x600, v62
	ds_read2_b32 v[190:191], v190 offset0:92 offset1:160
	ds_read_b96 v[194:196], v63 offset:896
	ds_read_b128 v[222:225], v45 offset:52512
	s_waitcnt lgkmcnt(7)
	v_mul_f32_e32 v4, v202, v206
	v_cndmask_b32_e64 v0, v202, v4, s[4:5]
	s_waitcnt lgkmcnt(6)
	v_fma_f32 v4, v14, v210, 0
	v_fma_f32 v8, v211, v15, 0
	v_add_f32_e32 v4, v4, v8
	s_nop 0
	v_fma_f32 v10, v14, v212, 0
	v_add_f32_dpp v4, v4, v4 quad_perm:[1,0,3,2] row_mask:0xf bank_mask:0xf bound_ctrl:1
	v_fma_f32 v0, v199, v0, -v4
	ds_read_b128 v[198:201], v45 offset:52768
	v_mul_f32_e32 v4, v203, v207
	v_cndmask_b32_e64 v1, v203, v4, s[4:5]
	s_waitcnt lgkmcnt(6)
	v_mul_f32_e32 v8, v0, v218
	v_cndmask_b32_e64 v8, 0, v8, s[6:7]
	v_fma_f32 v11, v15, v213, 0
	ds_read_b128 v[210:213], v63 offset:1024
	v_add_f32_e32 v8, v10, v8
	v_add_f32_e32 v8, v11, v8
	s_nop 1
	v_add_f32_dpp v8, v8, v8 quad_perm:[1,0,3,2] row_mask:0xf bank_mask:0xf bound_ctrl:1
	s_waitcnt lgkmcnt(6)
	v_fma_f32 v1, v214, v1, -v8
	v_cndmask_b32_e64 v16, v1, v0, s[6:7]
	v_mul_f32_e32 v0, v204, v208
	v_cndmask_b32_e64 v4, v204, v0, s[4:5]
	s_waitcnt lgkmcnt(5)
	v_fma_f32 v0, v14, v186, 0
	v_fma_f32 v1, v15, v187, 0
	v_fmac_f32_e32 v0, v188, v16
	v_add_u32_e32 v186, 0x800, v62
	ds_read2_b32 v[186:187], v186 offset0:100 offset1:168
	v_add_f32_e32 v0, v1, v0
	s_nop 1
	v_add_f32_dpp v0, v0, v0 quad_perm:[1,0,3,2] row_mask:0xf bank_mask:0xf bound_ctrl:1
	v_fma_f32 v4, v215, v4, -v0
	v_mul_f32_e32 v0, v205, v209
	v_cndmask_b32_e64 v3, v205, v0, s[4:5]
	ds_read_b128 v[202:205], v63 offset:1152
	ds_read2_b32 v[206:207], v24 offset0:36 offset1:101
	s_waitcnt lgkmcnt(6)
	v_fma_f32 v0, v14, v194, 0
	v_fmac_f32_e32 v0, v16, v196
	v_mul_f32_e32 v2, v4, v219
	v_cndmask_b32_e64 v2, 0, v2, s[6:7]
	v_fma_f32 v1, v15, v195, 0
	v_add_f32_e32 v0, v0, v2
	v_add_f32_e32 v0, v1, v0
	s_nop 1
	v_add_f32_dpp v0, v0, v0 quad_perm:[1,0,3,2] row_mask:0xf bank_mask:0xf bound_ctrl:1
	v_fma_f32 v0, v190, v3, -v0
	v_cndmask_b32_e64 v17, v0, v4, s[6:7]
	ds_read_b128 v[194:197], v63 offset:1280
	s_waitcnt lgkmcnt(5)
	v_mul_f32_e32 v4, v222, v198
	v_cndmask_b32_e64 v0, v222, v4, s[4:5]
	s_waitcnt lgkmcnt(4)
	v_fma_f32 v4, v14, v210, 0
	v_fma_f32 v8, v15, v211, 0
	v_fmac_f32_e32 v4, v16, v212
	v_fmac_f32_e32 v8, v17, v213
	v_add_f32_e32 v4, v4, v8
	s_nop 1
	v_add_f32_dpp v4, v4, v4 quad_perm:[1,0,3,2] row_mask:0xf bank_mask:0xf bound_ctrl:1
	v_fma_f32 v12, v191, v0, -v4
	v_mul_f32_e32 v0, v223, v199
	v_cndmask_b32_e64 v13, v223, v0, s[4:5]
	s_waitcnt lgkmcnt(2)
	v_fma_f32 v8, v14, v202, 0
	s_waitcnt lgkmcnt(1)
	v_mul_f32_e32 v4, v12, v206
	v_fma_f32 v9, v15, v203, 0
	v_fmac_f32_e32 v8, v16, v204
	v_cndmask_b32_e64 v4, 0, v4, s[6:7]
	v_fmac_f32_e32 v9, v17, v205
	v_add_f32_e32 v4, v8, v4
	v_add_f32_e32 v4, v9, v4
	s_nop 0
	s_nop 0
	v_add_f32_dpp v4, v4, v4 quad_perm:[1,0,3,2] row_mask:0xf bank_mask:0xf bound_ctrl:1
	v_fma_f32 v0, v186, v13, -v4
	v_cndmask_b32_e64 v18, v0, v12, s[6:7]
	v_mul_f32_e32 v0, v224, v200
	v_add_u32_e32 v6, 0x400, v63
	ds_read2_b32 v[218:219], v6 offset0:68 offset1:100
	v_add_u32_e32 v190, 0xa00, v62
	ds_read2_b32 v[190:191], v190 offset0:108 offset1:176
	ds_read_b128 v[202:205], v63 offset:1408
	ds_read_b128 v[210:213], v45 offset:52528
	ds_read_b128 v[214:217], v45 offset:52784
	v_cndmask_b32_e64 v0, v224, v0, s[4:5]
	s_waitcnt lgkmcnt(5)
	v_fma_f32 v2, v14, v194, 0
	v_fma_f32 v4, v15, v195, 0
	v_fmac_f32_e32 v2, v16, v196
	v_fmac_f32_e32 v4, v17, v197
	ds_read_b128 v[194:197], v63 offset:1536
	s_waitcnt lgkmcnt(5)
; __device__ void ph_dnpre(const P& p, float* lds) {
;     ...
;       for (int i = 0; i < 64; ++i) {
;         float sc = sBeta[i];
;         if (c >= 64) sc *= sEG[i];
;         const float rhs = col[i * LS] * sc;
;         float a0 = 0.f, a1 = 0.f;
; #pragma unroll
;         for (int jj = 0; 2 * jj + 1 < i; ++jj) {
;           const float l = Lp[i * 32 + jj];
;           if (jj & 1) a1 += l * xe[jj]; else a0 += l * xe[jj];
;         }
;         if (i & 1) {
;           const float l = B0[i * 32 + (i >> 1)];
;           a0 += (par == 0) ? l * xe[i >> 1] : 0.f;
;         }
;         float acc = a0 + a1;
;         acc += dpp_f<DPP_XOR1>(acc);
;         const float xi = rhs - acc;
;         if ((i & 1) == 0) xe[i >> 1] = xi;
;         else xe[i >> 1] = (par == 1) ? xi : xe[i >> 1];
;       }
	v_fmac_f32_e32 v2, v18, v218
	v_add_f32_e32 v2, v4, v2
	s_nop 1
	v_add_f32_dpp v2, v2, v2 quad_perm:[1,0,3,2] row_mask:0xf bank_mask:0xf bound_ctrl:1
	v_fma_f32 v4, v187, v0, -v2
	ds_read2_b64 v[186:189], v63 offset0:194 offset1:210
	v_mul_f32_e32 v0, v225, v201
	v_cndmask_b32_e64 v6, v225, v0, s[4:5]
	v_add_u32_e32 v198, 0xc00, v62
	ds_read2_b32 v[198:199], v198 offset0:116 offset1:184
	ds_read_b128 v[222:225], v63 offset:1664
	s_waitcnt lgkmcnt(6)
	v_fma_f32 v0, v14, v202, 0
	v_fmac_f32_e32 v0, v16, v204
	v_mul_f32_e32 v2, v4, v207
	v_fma_f32 v1, v15, v203, 0
	v_fmac_f32_e32 v0, v18, v219
	v_cndmask_b32_e64 v2, 0, v2, s[6:7]
	v_fmac_f32_e32 v1, v17, v205
	v_add_f32_e32 v0, v0, v2
	v_add_f32_e32 v0, v1, v0
	s_nop 1
	v_add_f32_dpp v0, v0, v0 quad_perm:[1,0,3,2] row_mask:0xf bank_mask:0xf bound_ctrl:1
	v_fma_f32 v0, v190, v6, -v0
	v_cndmask_b32_e64 v19, v0, v4, s[6:7]
	ds_read2_b32 v[218:219], v24 offset0:166 offset1:231
	ds_read_b128 v[202:205], v63 offset:1792
	ds_read_b96 v[206:208], v63 offset:1808
	s_waitcnt lgkmcnt(7)
	v_mul_f32_e32 v4, v210, v214
	v_cndmask_b32_e64 v0, v210, v4, s[4:5]
	s_waitcnt lgkmcnt(6)
	v_fma_f32 v4, v14, v194, 0
	v_fma_f32 v12, v15, v195, 0
	v_fmac_f32_e32 v4, v16, v196
	v_fmac_f32_e32 v12, v17, v197
	v_add_u32_e32 v194, 0xe00, v62
	ds_read2_b32 v[194:195], v194 offset0:124 offset1:192
	s_waitcnt lgkmcnt(6)
	v_fmac_f32_e32 v4, v18, v186
	v_fmac_f32_e32 v12, v19, v187
	v_add_f32_e32 v4, v4, v12
	s_nop 1
	v_add_f32_dpp v4, v4, v4 quad_perm:[1,0,3,2] row_mask:0xf bank_mask:0xf bound_ctrl:1
	v_fma_f32 v0, v191, v0, -v4
	v_mul_f32_e32 v4, v211, v215
	v_cndmask_b32_e64 v1, v211, v4, s[4:5]
	ds_read_b128 v[190:193], v63 offset:1920
	v_add_u32_e32 v24, 0x1400, v62
	s_waitcnt lgkmcnt(5)
	v_fma_f32 v8, v14, v222, 0
	v_fmac_f32_e32 v8, v16, v224
	v_fma_f32 v9, v15, v223, 0
	v_fmac_f32_e32 v8, v18, v188
	s_waitcnt lgkmcnt(4)
	v_mul_f32_e32 v10, v0, v218
	v_fmac_f32_e32 v9, v17, v225
	ds_read_b96 v[222:224], v63 offset:1936
	v_cndmask_b32_e64 v10, 0, v10, s[6:7]
	v_fmac_f32_e32 v9, v19, v189
	ds_read_b128 v[186:189], v45 offset:52544
	v_add_f32_e32 v8, v8, v10
	v_add_f32_e32 v8, v9, v8
	s_nop 1
	v_add_f32_dpp v8, v8, v8 quad_perm:[1,0,3,2] row_mask:0xf bank_mask:0xf bound_ctrl:1
	v_fma_f32 v1, v198, v1, -v8
	v_cndmask_b32_e64 v20, v1, v0, s[6:7]
	v_mul_f32_e32 v0, v212, v216
	v_cndmask_b32_e64 v4, v212, v0, s[4:5]
	s_waitcnt lgkmcnt(5)
	v_fma_f32 v6, v14, v202, 0
	v_fma_f32 v8, v15, v203, 0
	v_fmac_f32_e32 v6, v16, v204
	v_fmac_f32_e32 v8, v17, v205
	ds_read_b128 v[202:205], v45 offset:52800
	s_waitcnt lgkmcnt(5)
	v_fmac_f32_e32 v6, v18, v206
	v_fmac_f32_e32 v8, v19, v207
	v_fmac_f32_e32 v6, v20, v208
	ds_read_b128 v[206:209], v63 offset:2048
	v_add_f32_e32 v0, v8, v6
	s_nop 1
	v_add_f32_dpp v0, v0, v0 quad_perm:[1,0,3,2] row_mask:0xf bank_mask:0xf bound_ctrl:1
	v_fma_f32 v4, v199, v4, -v0
	v_mul_f32_e32 v0, v213, v217
	v_cndmask_b32_e64 v5, v213, v0, s[4:5]
	ds_read_b128 v[198:201], v63 offset:2064
	v_add_u32_e32 v210, 0x1000, v62
	ds_read2_b32 v[210:211], v210 offset0:132 offset1:200
	s_waitcnt lgkmcnt(6)
	v_fma_f32 v6, v14, v190, 0
	v_fma_f32 v7, v15, v191, 0
	v_fmac_f32_e32 v6, v16, v192
	ds_read_b128 v[214:217], v63 offset:2176
	v_fmac_f32_e32 v7, v17, v193
	s_waitcnt lgkmcnt(6)
	v_fmac_f32_e32 v6, v18, v222
	v_mul_f32_e32 v0, v4, v219
	v_fmac_f32_e32 v6, v20, v224
	v_cndmask_b32_e64 v0, 0, v0, s[6:7]
	v_fmac_f32_e32 v7, v19, v223
	v_add_f32_e32 v0, v6, v0
	v_add_f32_e32 v0, v7, v0
	s_nop 1
	v_add_f32_dpp v0, v0, v0 quad_perm:[1,0,3,2] row_mask:0xf bank_mask:0xf bound_ctrl:1
	v_fma_f32 v0, v194, v5, -v0
	v_cndmask_b32_e64 v21, v0, v4, s[6:7]
	ds_read2_b32 v[218:219], v28 offset0:40 offset1:105
	ds_read_b128 v[190:193], v63 offset:2192
	ds_read_b128 v[222:225], v63 offset:2304
	s_waitcnt lgkmcnt(7)
	v_mul_f32_e32 v4, v186, v202
	v_cndmask_b32_e64 v0, v186, v4, s[4:5]
	s_waitcnt lgkmcnt(6)
	v_fma_f32 v4, v14, v206, 0
	v_fma_f32 v12, v15, v207, 0
	v_fmac_f32_e32 v4, v16, v208
	v_fmac_f32_e32 v12, v17, v209
	ds_read_b128 v[206:209], v63 offset:2320
	s_waitcnt lgkmcnt(6)
	v_fmac_f32_e32 v4, v18, v198
	v_fmac_f32_e32 v12, v19, v199
	v_fmac_f32_e32 v4, v20, v200
	v_fmac_f32_e32 v12, v21, v201
	v_add_f32_e32 v4, v4, v12
	s_nop 1
	v_add_f32_dpp v4, v4, v4 quad_perm:[1,0,3,2] row_mask:0xf bank_mask:0xf bound_ctrl:1
	v_fma_f32 v12, v195, v0, -v4
	v_mul_f32_e32 v0, v187, v203
	v_cndmask_b32_e64 v13, v187, v0, s[4:5]
	ds_read2_b32 v[194:195], v29 offset0:72 offset1:104
	ds_read2_b32 v[198:199], v24 offset0:12 offset1:80
	s_waitcnt lgkmcnt(6)
	v_fma_f32 v22, v14, v214, 0
	v_fma_f32 v23, v15, v215, 0
	v_fmac_f32_e32 v22, v16, v216
	v_fmac_f32_e32 v23, v17, v217
	ds_read_b128 v[214:217], v63 offset:2432
	s_waitcnt lgkmcnt(6)
	v_mul_f32_e32 v4, v12, v218
	v_cndmask_b32_e64 v4, 0, v4, s[6:7]
	s_waitcnt lgkmcnt(5)
	v_fmac_f32_e32 v22, v18, v190
	v_fmac_f32_e32 v23, v19, v191
	v_fmac_f32_e32 v22, v20, v192
	v_fmac_f32_e32 v23, v21, v193
	ds_read_b128 v[190:193], v63 offset:2448
	v_add_f32_e32 v4, v22, v4
	s_nop 0
	v_add_f32_e32 v4, v23, v4
	s_nop 1
	v_add_f32_dpp v4, v4, v4 quad_perm:[1,0,3,2] row_mask:0xf bank_mask:0xf bound_ctrl:1
	v_fma_f32 v0, v210, v13, -v4
	v_cndmask_b32_e64 v22, v0, v12, s[6:7]
	v_mul_f32_e32 v0, v188, v204
	v_cndmask_b32_e64 v0, v188, v0, s[4:5]
	s_waitcnt lgkmcnt(5)
	v_fma_f32 v2, v14, v222, 0
	v_fma_f32 v4, v15, v223, 0
	v_fmac_f32_e32 v2, v16, v224
	v_fmac_f32_e32 v4, v17, v225
	ds_read_b128 v[222:225], v45 offset:52560
	s_waitcnt lgkmcnt(5)
	v_fmac_f32_e32 v2, v18, v206
	v_fmac_f32_e32 v4, v19, v207
	v_fmac_f32_e32 v2, v20, v208
	v_fmac_f32_e32 v4, v21, v209
	ds_read_b128 v[206:209], v45 offset:52816
	s_waitcnt lgkmcnt(5)
; __device__ void ph_dnpre(const P& p, float* lds) {
;     ...
;       for (int i = 0; i < 64; ++i) {
;         float sc = sBeta[i];
;         if (c >= 64) sc *= sEG[i];
;         const float rhs = col[i * LS] * sc;
;         float a0 = 0.f, a1 = 0.f;
; #pragma unroll
;         for (int jj = 0; 2 * jj + 1 < i; ++jj) {
;           const float l = Lp[i * 32 + jj];
;           if (jj & 1) a1 += l * xe[jj]; else a0 += l * xe[jj];
;         }
;         if (i & 1) {
;           const float l = B0[i * 32 + (i >> 1)];
;           a0 += (par == 0) ? l * xe[i >> 1] : 0.f;
;         }
;         float acc = a0 + a1;
;         acc += dpp_f<DPP_XOR1>(acc);
;         const float xi = rhs - acc;
;         if ((i & 1) == 0) xe[i >> 1] = xi;
;         else xe[i >> 1] = (par == 1) ? xi : xe[i >> 1];
;       }
	v_fmac_f32_e32 v2, v22, v194
	v_add_f32_e32 v2, v4, v2
	s_nop 1
	v_add_f32_dpp v2, v2, v2 quad_perm:[1,0,3,2] row_mask:0xf bank_mask:0xf bound_ctrl:1
	v_fma_f32 v4, v211, v0, -v2
	ds_read_b128 v[210:213], v63 offset:2560
	v_mul_f32_e32 v0, v189, v205
	v_cndmask_b32_e64 v6, v189, v0, s[4:5]
	ds_read_b128 v[186:189], v63 offset:2576
	ds_read2_b64 v[202:205], v29 offset0:68 offset1:84
	s_waitcnt lgkmcnt(6)
	v_fma_f32 v7, v14, v214, 0
	v_fma_f32 v8, v15, v215, 0
	v_fmac_f32_e32 v7, v16, v216
	v_fmac_f32_e32 v8, v17, v217
	ds_read2_b32 v[214:215], v24 offset0:148 offset1:216
	s_waitcnt lgkmcnt(6)
	v_fmac_f32_e32 v7, v18, v190
	v_fmac_f32_e32 v7, v20, v192
	v_mul_f32_e32 v0, v4, v219
	v_fmac_f32_e32 v8, v19, v191
	v_fmac_f32_e32 v7, v22, v195
	v_cndmask_b32_e64 v0, 0, v0, s[6:7]
	v_fmac_f32_e32 v8, v21, v193
	v_add_f32_e32 v0, v7, v0
	v_add_f32_e32 v0, v8, v0
	s_nop 1
	v_add_f32_dpp v0, v0, v0 quad_perm:[1,0,3,2] row_mask:0xf bank_mask:0xf bound_ctrl:1
	v_fma_f32 v0, v198, v6, -v0
	v_cndmask_b32_e64 v23, v0, v4, s[6:7]
	ds_read_b128 v[190:193], v63 offset:2688
	ds_read2_b32 v[218:219], v28 offset0:170 offset1:235
	ds_read_b128 v[194:197], v63 offset:2704
	s_waitcnt lgkmcnt(7)
	v_mul_f32_e32 v4, v222, v206
	v_cndmask_b32_e64 v0, v222, v4, s[4:5]
	s_waitcnt lgkmcnt(6)
	v_fma_f32 v4, v14, v210, 0
	v_fma_f32 v12, v15, v211, 0
	v_fmac_f32_e32 v4, v16, v212
	v_fmac_f32_e32 v12, v17, v213
	ds_read_b128 v[210:213], v63 offset:2816
	s_waitcnt lgkmcnt(6)
	v_fmac_f32_e32 v4, v18, v186
	v_fmac_f32_e32 v12, v19, v187
	v_fmac_f32_e32 v4, v20, v188
	v_fmac_f32_e32 v12, v21, v189
	ds_read_b96 v[186:188], v63 offset:2848
	s_waitcnt lgkmcnt(6)
	v_fmac_f32_e32 v4, v22, v202
	v_fmac_f32_e32 v12, v23, v203
	v_add_f32_e32 v4, v4, v12
	s_nop 1
	v_add_f32_dpp v4, v4, v4 quad_perm:[1,0,3,2] row_mask:0xf bank_mask:0xf bound_ctrl:1
	v_fma_f32 v0, v199, v0, -v4
	v_mul_f32_e32 v4, v223, v207
	v_cndmask_b32_e64 v1, v223, v4, s[4:5]
	ds_read_b128 v[198:201], v63 offset:2832
	v_add_u32_e32 v28, 0x1c00, v62
	s_waitcnt lgkmcnt(5)
	v_fma_f32 v8, v14, v190, 0
	v_fma_f32 v9, v15, v191, 0
	v_fmac_f32_e32 v8, v16, v192
	v_fmac_f32_e32 v9, v17, v193
	s_waitcnt lgkmcnt(3)
	v_fmac_f32_e32 v8, v18, v194
	v_fmac_f32_e32 v8, v20, v196
	v_fmac_f32_e32 v9, v19, v195
	v_fmac_f32_e32 v8, v22, v204
	v_mul_f32_e32 v10, v0, v218
	v_fmac_f32_e32 v9, v21, v197
	v_cndmask_b32_e64 v10, 0, v10, s[6:7]
	v_fmac_f32_e32 v9, v23, v205
	v_add_f32_e32 v8, v8, v10
	v_add_f32_e32 v8, v9, v8
	s_nop 1
	v_add_f32_dpp v8, v8, v8 quad_perm:[1,0,3,2] row_mask:0xf bank_mask:0xf bound_ctrl:1
	v_fma_f32 v1, v214, v1, -v8
	v_cndmask_b32_e64 v24, v1, v0, s[6:7]
	v_mul_f32_e32 v0, v224, v208
	v_cndmask_b32_e64 v4, v224, v0, s[4:5]
	s_waitcnt lgkmcnt(2)
	v_fma_f32 v6, v14, v210, 0
	v_fma_f32 v12, v15, v211, 0
	v_fmac_f32_e32 v6, v16, v212
	v_fmac_f32_e32 v12, v17, v213
	s_waitcnt lgkmcnt(0)
	v_fmac_f32_e32 v6, v18, v198
	v_fmac_f32_e32 v12, v19, v199
	v_fmac_f32_e32 v6, v20, v200
	v_fmac_f32_e32 v12, v21, v201
	v_fmac_f32_e32 v6, v22, v186
	v_fmac_f32_e32 v12, v23, v187
	v_fmac_f32_e32 v6, v24, v188
	v_add_f32_e32 v0, v12, v6
	v_add_u32_e32 v12, 0x1800, v62
	ds_read2_b32 v[186:187], v12 offset0:28 offset1:96
	ds_read_b128 v[190:193], v63 offset:2944
	ds_read_b128 v[194:197], v63 offset:2960
	ds_read_b96 v[198:200], v63 offset:2976
	ds_read_b128 v[202:205], v45 offset:52576
	ds_read_b128 v[210:213], v45 offset:52832
	s_nop 0
	v_add_f32_dpp v0, v0, v0 quad_perm:[1,0,3,2] row_mask:0xf bank_mask:0xf bound_ctrl:1
	v_fma_f32 v4, v215, v4, -v0
	v_mul_f32_e32 v0, v225, v209
	v_cndmask_b32_e64 v5, v225, v0, s[4:5]
	ds_read_b128 v[206:209], v63 offset:3072
	ds_read_b128 v[214:217], v63 offset:3088
	s_waitcnt lgkmcnt(6)
	v_fma_f32 v6, v14, v190, 0
	v_fma_f32 v7, v15, v191, 0
	v_fmac_f32_e32 v6, v16, v192
	v_fmac_f32_e32 v7, v17, v193
	ds_read_b128 v[190:193], v63 offset:3104
	s_waitcnt lgkmcnt(6)
	v_fmac_f32_e32 v6, v18, v194
	v_fmac_f32_e32 v7, v19, v195
	v_fmac_f32_e32 v6, v20, v196
	ds_read2_b32 v[222:223], v12 offset0:164 offset1:232
	v_fmac_f32_e32 v7, v21, v197
	s_waitcnt lgkmcnt(6)
	v_fmac_f32_e32 v6, v22, v198
	v_mul_f32_e32 v0, v4, v219
	v_fmac_f32_e32 v6, v24, v200
	v_cndmask_b32_e64 v0, 0, v0, s[6:7]
	v_fmac_f32_e32 v7, v23, v199
	v_add_f32_e32 v0, v6, v0
	v_add_f32_e32 v0, v7, v0
	s_nop 1
	v_add_f32_dpp v0, v0, v0 quad_perm:[1,0,3,2] row_mask:0xf bank_mask:0xf bound_ctrl:1
	v_fma_f32 v0, v186, v5, -v0
	v_cndmask_b32_e64 v25, v0, v4, s[6:7]
	ds_read_b128 v[194:197], v63 offset:3200
	ds_read2_b32 v[218:219], v32 offset0:44 offset1:109
	ds_read_b128 v[198:201], v63 offset:3216
	s_waitcnt lgkmcnt(7)
	v_mul_f32_e32 v4, v202, v210
	v_cndmask_b32_e64 v0, v202, v4, s[4:5]
	s_waitcnt lgkmcnt(6)
	v_fma_f32 v4, v14, v206, 0
	v_fma_f32 v13, v15, v207, 0
	v_fmac_f32_e32 v4, v16, v208
	v_fmac_f32_e32 v13, v17, v209
	ds_read_b128 v[206:209], v63 offset:3232
	s_waitcnt lgkmcnt(6)
	v_fmac_f32_e32 v4, v18, v214
	v_fmac_f32_e32 v13, v19, v215
	v_fmac_f32_e32 v4, v20, v216
	v_fmac_f32_e32 v13, v21, v217
	ds_read_b128 v[214:217], v63 offset:3328
	s_waitcnt lgkmcnt(6)
	v_fmac_f32_e32 v4, v22, v190
	v_fmac_f32_e32 v13, v23, v191
	v_fmac_f32_e32 v4, v24, v192
	v_fmac_f32_e32 v13, v25, v193
	v_add_f32_e32 v4, v4, v13
	s_nop 1
	v_add_f32_dpp v4, v4, v4 quad_perm:[1,0,3,2] row_mask:0xf bank_mask:0xf bound_ctrl:1
	v_fma_f32 v13, v187, v0, -v4
	v_mul_f32_e32 v0, v203, v211
	v_cndmask_b32_e64 v26, v203, v0, s[4:5]
	ds_read_b128 v[186:189], v63 offset:3344
	ds_read_b128 v[190:193], v63 offset:3360
	s_waitcnt lgkmcnt(6)
	v_fma_f32 v12, v14, v194, 0
	v_fma_f32 v27, v15, v195, 0
	v_fmac_f32_e32 v12, v16, v196
	v_fmac_f32_e32 v27, v17, v197
	s_waitcnt lgkmcnt(5)
; __device__ void ph_dnpre(const P& p, float* lds) {
;     ...
;       const int c = tid >> 1, par = tid & 1;
;       float xe[32];
;       float* col = c < 64 ? (B2 + c) : (B1 + c - 64);
;       const float* Lp = B0 + par * 2048;
; #pragma unroll
;       for (int i = 0; i < 64; ++i) {
;         float sc = sBeta[i];
;         if (c >= 64) sc *= sEG[i];
;         const float rhs = col[i * LS] * sc;
;         float a0 = 0.f, a1 = 0.f;
; #pragma unroll
;         for (int jj = 0; 2 * jj + 1 < i; ++jj) {
;           const float l = Lp[i * 32 + jj];
;           if (jj & 1) a1 += l * xe[jj]; else a0 += l * xe[jj];
;         }
;         if (i & 1) {
;           const float l = B0[i * 32 + (i >> 1)];
;           a0 += (par == 0) ? l * xe[i >> 1] : 0.f;
;         }
;         float acc = a0 + a1;
;         acc += dpp_f<DPP_XOR1>(acc);
;         const float xi = rhs - acc;
;         if ((i & 1) == 0) xe[i >> 1] = xi;
;         else xe[i >> 1] = (par == 1) ? xi : xe[i >> 1];
;       }
	v_mul_f32_e32 v4, v13, v218
	v_cndmask_b32_e64 v4, 0, v4, s[6:7]
	s_waitcnt lgkmcnt(4)
	v_fmac_f32_e32 v12, v18, v198
	v_fmac_f32_e32 v27, v19, v199
	v_fmac_f32_e32 v12, v20, v200
	v_fmac_f32_e32 v27, v21, v201
	s_waitcnt lgkmcnt(3)
	v_fmac_f32_e32 v12, v22, v206
	v_fmac_f32_e32 v27, v23, v207
	v_fmac_f32_e32 v12, v24, v208
	v_fmac_f32_e32 v27, v25, v209
	v_add_f32_e32 v4, v12, v4
	s_nop 0
	v_add_f32_e32 v4, v27, v4
	s_nop 1
	v_add_f32_dpp v4, v4, v4 quad_perm:[1,0,3,2] row_mask:0xf bank_mask:0xf bound_ctrl:1
	v_fma_f32 v0, v222, v26, -v4
	v_cndmask_b32_e64 v26, v0, v13, s[6:7]
	v_mul_f32_e32 v0, v204, v212
	v_cndmask_b32_e64 v0, v204, v0, s[4:5]
	s_waitcnt lgkmcnt(2)
	v_fma_f32 v2, v14, v214, 0
	v_fma_f32 v4, v15, v215, 0
	v_fmac_f32_e32 v2, v16, v216
	v_fmac_f32_e32 v4, v17, v217
	v_add_u32_e32 v6, 0xc00, v63
	ds_read2_b32 v[194:195], v6 offset0:76 offset1:108
	ds_read2_b32 v[198:199], v28 offset0:44 offset1:112
	ds_read_b128 v[206:209], v63 offset:3456
	ds_read_b128 v[214:217], v63 offset:3472
	s_waitcnt lgkmcnt(5)
	v_fmac_f32_e32 v2, v18, v186
	v_fmac_f32_e32 v4, v19, v187
	v_fmac_f32_e32 v2, v20, v188
	v_fmac_f32_e32 v4, v21, v189
	ds_read_b128 v[186:189], v63 offset:3488
	s_waitcnt lgkmcnt(5)
	v_fmac_f32_e32 v2, v22, v190
	v_fmac_f32_e32 v4, v23, v191
	v_fmac_f32_e32 v2, v24, v192
	v_fmac_f32_e32 v4, v25, v193
	ds_read_b128 v[190:193], v45 offset:52592
	s_waitcnt lgkmcnt(5)
	v_fmac_f32_e32 v2, v26, v194
	v_add_f32_e32 v2, v4, v2
	s_nop 1
	v_add_f32_dpp v2, v2, v2 quad_perm:[1,0,3,2] row_mask:0xf bank_mask:0xf bound_ctrl:1
	v_fma_f32 v4, v223, v0, -v2
	ds_read_b128 v[222:225], v45 offset:52848
	v_mul_f32_e32 v0, v205, v213
	v_cndmask_b32_e64 v6, v205, v0, s[4:5]
	ds_read_b128 v[202:205], v63 offset:3584
	ds_read_b128 v[210:213], v63 offset:3600
	s_waitcnt lgkmcnt(6)
	v_fma_f32 v7, v14, v206, 0
	v_fma_f32 v8, v15, v207, 0
	v_fmac_f32_e32 v7, v16, v208
	v_fmac_f32_e32 v8, v17, v209
	ds_read_b128 v[206:209], v63 offset:3616
	s_waitcnt lgkmcnt(6)
	v_fmac_f32_e32 v7, v18, v214
	v_fmac_f32_e32 v8, v19, v215
	v_fmac_f32_e32 v7, v20, v216
	v_fmac_f32_e32 v8, v21, v217
	ds_read2_b64 v[214:217], v29 offset0:198 offset1:214
	s_waitcnt lgkmcnt(6)
	v_fmac_f32_e32 v7, v22, v186
	v_fmac_f32_e32 v7, v24, v188
	v_mul_f32_e32 v0, v4, v219
	v_fmac_f32_e32 v8, v23, v187
	v_fmac_f32_e32 v7, v26, v195
	v_cndmask_b32_e64 v0, 0, v0, s[6:7]
	v_fmac_f32_e32 v8, v25, v189
	v_add_f32_e32 v0, v7, v0
	v_add_f32_e32 v0, v8, v0
	s_nop 1
	v_add_f32_dpp v0, v0, v0 quad_perm:[1,0,3,2] row_mask:0xf bank_mask:0xf bound_ctrl:1
	v_fma_f32 v0, v198, v6, -v0
	v_cndmask_b32_e64 v27, v0, v4, s[6:7]
	ds_read2_b32 v[218:219], v28 offset0:180 offset1:248
	ds_read_b128 v[186:189], v63 offset:3712
	ds_read2_b32 v[194:195], v32 offset0:174 offset1:239
	s_waitcnt lgkmcnt(7)
	v_mul_f32_e32 v4, v190, v222
	v_cndmask_b32_e64 v0, v190, v4, s[4:5]
	s_waitcnt lgkmcnt(6)
	v_fma_f32 v4, v14, v202, 0
	v_fma_f32 v12, v15, v203, 0
	v_fmac_f32_e32 v4, v16, v204
	v_fmac_f32_e32 v12, v17, v205
	ds_read_b128 v[202:205], v63 offset:3728
	s_waitcnt lgkmcnt(6)
	v_fmac_f32_e32 v4, v18, v210
	v_fmac_f32_e32 v12, v19, v211
	v_fmac_f32_e32 v4, v20, v212
	v_fmac_f32_e32 v12, v21, v213
	ds_read_b128 v[210:213], v63 offset:3744
	s_waitcnt lgkmcnt(6)
	v_fmac_f32_e32 v4, v22, v206
	v_fmac_f32_e32 v12, v23, v207
	v_fmac_f32_e32 v4, v24, v208
	v_fmac_f32_e32 v12, v25, v209
	ds_read_b128 v[206:209], v63 offset:3840
	s_waitcnt lgkmcnt(6)
	v_fmac_f32_e32 v4, v26, v214
	v_fmac_f32_e32 v12, v27, v215
	v_add_f32_e32 v4, v4, v12
	s_nop 1
	v_add_f32_dpp v4, v4, v4 quad_perm:[1,0,3,2] row_mask:0xf bank_mask:0xf bound_ctrl:1
	v_fma_f32 v0, v199, v0, -v4
	v_mul_f32_e32 v4, v191, v223
	v_cndmask_b32_e64 v1, v191, v4, s[4:5]
	ds_read_b96 v[198:200], v63 offset:3888
	s_waitcnt lgkmcnt(5)
	v_fma_f32 v8, v14, v186, 0
	v_fma_f32 v9, v15, v187, 0
	v_fmac_f32_e32 v8, v16, v188
	v_fmac_f32_e32 v9, v17, v189
	ds_read_b128 v[186:189], v63 offset:3856
	s_waitcnt lgkmcnt(4)
	v_fmac_f32_e32 v8, v18, v202
	v_fmac_f32_e32 v9, v19, v203
	v_fmac_f32_e32 v8, v20, v204
	v_fmac_f32_e32 v9, v21, v205
	ds_read_b128 v[202:205], v63 offset:3872
	s_waitcnt lgkmcnt(4)
	v_fmac_f32_e32 v8, v22, v210
	v_fmac_f32_e32 v8, v24, v212
	v_fmac_f32_e32 v9, v23, v211
	v_fmac_f32_e32 v8, v26, v216
	v_mul_f32_e32 v10, v0, v194
	v_fmac_f32_e32 v9, v25, v213
	v_add_u32_e32 v210, 0x2000, v62
	ds_read2_b32 v[210:211], v210 offset0:60 offset1:128
	v_cndmask_b32_e64 v10, 0, v10, s[6:7]
	v_fmac_f32_e32 v9, v27, v217
	ds_read_b128 v[214:217], v63 offset:3968
	v_add_f32_e32 v8, v8, v10
	v_add_f32_e32 v8, v9, v8
	s_nop 1
	v_add_f32_dpp v8, v8, v8 quad_perm:[1,0,3,2] row_mask:0xf bank_mask:0xf bound_ctrl:1
	v_fma_f32 v1, v218, v1, -v8
	v_cndmask_b32_e64 v28, v1, v0, s[6:7]
	v_mul_f32_e32 v0, v192, v224
	v_cndmask_b32_e64 v4, v192, v0, s[4:5]
	s_waitcnt lgkmcnt(5)
	v_fma_f32 v6, v14, v206, 0
	v_fma_f32 v12, v15, v207, 0
	v_fmac_f32_e32 v6, v16, v208
	v_fmac_f32_e32 v12, v17, v209
	ds_read_b128 v[206:209], v63 offset:3984
	s_waitcnt lgkmcnt(4)
	v_fmac_f32_e32 v6, v18, v186
	v_fmac_f32_e32 v12, v19, v187
	v_fmac_f32_e32 v6, v20, v188
	v_fmac_f32_e32 v12, v21, v189
	ds_read_b128 v[186:189], v63 offset:4000
	s_waitcnt lgkmcnt(4)
	v_fmac_f32_e32 v6, v22, v202
	v_fmac_f32_e32 v12, v23, v203
	v_fmac_f32_e32 v6, v24, v204
	v_fmac_f32_e32 v12, v25, v205
	ds_read_b96 v[202:204], v63 offset:4016
	v_fmac_f32_e32 v6, v26, v198
	v_fmac_f32_e32 v12, v27, v199
	v_fmac_f32_e32 v6, v28, v200
	ds_read_b128 v[198:201], v45 offset:52608
	v_add_f32_e32 v0, v12, v6
	s_nop 1
	v_add_f32_dpp v0, v0, v0 quad_perm:[1,0,3,2] row_mask:0xf bank_mask:0xf bound_ctrl:1
	v_fma_f32 v4, v219, v4, -v0
	v_mul_f32_e32 v0, v193, v225
	v_cndmask_b32_e64 v5, v193, v0, s[4:5]
	ds_read_b128 v[190:193], v45 offset:52864
	ds_read_b128 v[222:225], v63 offset:4096
	s_waitcnt lgkmcnt(6)
; __device__ void ph_dnpre(const P& p, float* lds) {
;     ...
;       const int c = tid >> 1, par = tid & 1;
;       float xe[32];
;       float* col = c < 64 ? (B2 + c) : (B1 + c - 64);
;       const float* Lp = B0 + par * 2048;
; #pragma unroll
;       for (int i = 0; i < 64; ++i) {
;         float sc = sBeta[i];
;         if (c >= 64) sc *= sEG[i];
;         const float rhs = col[i * LS] * sc;
;         float a0 = 0.f, a1 = 0.f;
; #pragma unroll
;         for (int jj = 0; 2 * jj + 1 < i; ++jj) {
;           const float l = Lp[i * 32 + jj];
;           if (jj & 1) a1 += l * xe[jj]; else a0 += l * xe[jj];
;         }
;         if (i & 1) {
;           const float l = B0[i * 32 + (i >> 1)];
;           a0 += (par == 0) ? l * xe[i >> 1] : 0.f;
;         }
;         float acc = a0 + a1;
;         acc += dpp_f<DPP_XOR1>(acc);
;         const float xi = rhs - acc;
;         if ((i & 1) == 0) xe[i >> 1] = xi;
;         else xe[i >> 1] = (par == 1) ? xi : xe[i >> 1];
;       }
	v_fma_f32 v6, v14, v214, 0
	v_fma_f32 v7, v15, v215, 0
	v_fmac_f32_e32 v6, v16, v216
	v_fmac_f32_e32 v7, v17, v217
	ds_read_b128 v[214:217], v63 offset:4112
	s_waitcnt lgkmcnt(6)
	v_fmac_f32_e32 v6, v18, v206
	v_fmac_f32_e32 v7, v19, v207
	v_fmac_f32_e32 v6, v20, v208
	v_fmac_f32_e32 v7, v21, v209
	ds_read_b128 v[206:209], v63 offset:4128
	s_waitcnt lgkmcnt(6)
	v_fmac_f32_e32 v6, v22, v186
	v_fmac_f32_e32 v7, v23, v187
	v_fmac_f32_e32 v6, v24, v188
	v_fmac_f32_e32 v7, v25, v189
	ds_read_b128 v[186:189], v63 offset:4144
	s_waitcnt lgkmcnt(6)
	v_fmac_f32_e32 v6, v26, v202
	v_mul_f32_e32 v0, v4, v195
	v_fmac_f32_e32 v6, v28, v204
	v_cndmask_b32_e64 v0, 0, v0, s[6:7]
	v_fmac_f32_e32 v7, v27, v203
	v_add_f32_e32 v0, v6, v0
	v_add_f32_e32 v0, v7, v0
	s_nop 1
	v_add_f32_dpp v0, v0, v0 quad_perm:[1,0,3,2] row_mask:0xf bank_mask:0xf bound_ctrl:1
	v_fma_f32 v0, v210, v5, -v0
	v_cndmask_b32_e64 v29, v0, v4, s[6:7]
	v_add_u32_e32 v218, 0x2200, v62
	ds_read2_b32 v[218:219], v218 offset0:68 offset1:136
	ds_read_b128 v[194:197], v63 offset:4224
	ds_read2_b32 v[202:203], v36 offset0:48 offset1:113
	s_waitcnt lgkmcnt(7)
	v_mul_f32_e32 v4, v198, v190
	v_cndmask_b32_e64 v0, v198, v4, s[4:5]
	s_waitcnt lgkmcnt(6)
	v_fma_f32 v4, v14, v222, 0
	v_fma_f32 v12, v15, v223, 0
	v_fmac_f32_e32 v4, v16, v224
	v_fmac_f32_e32 v12, v17, v225
	ds_read_b128 v[222:225], v63 offset:4240
	s_waitcnt lgkmcnt(6)
	v_fmac_f32_e32 v4, v18, v214
	v_fmac_f32_e32 v12, v19, v215
	v_fmac_f32_e32 v4, v20, v216
	v_fmac_f32_e32 v12, v21, v217
	ds_read_b128 v[214:217], v63 offset:4256
	s_waitcnt lgkmcnt(6)
	v_fmac_f32_e32 v4, v22, v206
	v_fmac_f32_e32 v12, v23, v207
	v_fmac_f32_e32 v4, v24, v208
	v_fmac_f32_e32 v12, v25, v209
	ds_read_b128 v[206:209], v63 offset:4272
	s_waitcnt lgkmcnt(6)
	v_fmac_f32_e32 v4, v26, v186
	v_fmac_f32_e32 v12, v27, v187
	v_fmac_f32_e32 v4, v28, v188
	v_fmac_f32_e32 v12, v29, v189
	v_add_f32_e32 v4, v4, v12
	s_nop 1
	v_add_f32_dpp v4, v4, v4 quad_perm:[1,0,3,2] row_mask:0xf bank_mask:0xf bound_ctrl:1
	v_fma_f32 v12, v211, v0, -v4
	v_mul_f32_e32 v0, v199, v191
	v_cndmask_b32_e64 v13, v199, v0, s[4:5]
	ds_read_b128 v[186:189], v63 offset:4352
	ds_read_b128 v[210:213], v63 offset:4368
	s_waitcnt lgkmcnt(6)
	v_fma_f32 v30, v14, v194, 0
	v_fma_f32 v31, v15, v195, 0
	v_fmac_f32_e32 v30, v16, v196
	v_fmac_f32_e32 v31, v17, v197
	ds_read_b128 v[194:197], v63 offset:4384
	s_waitcnt lgkmcnt(6)
	v_mul_f32_e32 v4, v12, v202
	v_cndmask_b32_e64 v4, 0, v4, s[6:7]
	s_waitcnt lgkmcnt(5)
	v_fmac_f32_e32 v30, v18, v222
	v_fmac_f32_e32 v31, v19, v223
	v_fmac_f32_e32 v30, v20, v224
	v_fmac_f32_e32 v31, v21, v225
	ds_read_b128 v[222:225], v63 offset:4400
	s_waitcnt lgkmcnt(5)
	v_fmac_f32_e32 v30, v22, v214
	v_fmac_f32_e32 v31, v23, v215
	v_fmac_f32_e32 v30, v24, v216
	v_fmac_f32_e32 v31, v25, v217
	ds_read2_b32 v[214:215], v37 offset0:80 offset1:112
	s_waitcnt lgkmcnt(5)
	v_fmac_f32_e32 v30, v26, v206
	v_fmac_f32_e32 v31, v27, v207
	v_fmac_f32_e32 v30, v28, v208
	v_fmac_f32_e32 v31, v29, v209
	v_add_u32_e32 v206, 0x2400, v62
	ds_read2_b32 v[206:207], v206 offset0:76 offset1:144
	v_add_f32_e32 v4, v30, v4
	s_nop 0
	v_add_f32_e32 v4, v31, v4
	s_nop 1
	v_add_f32_dpp v4, v4, v4 quad_perm:[1,0,3,2] row_mask:0xf bank_mask:0xf bound_ctrl:1
	v_fma_f32 v0, v218, v13, -v4
	v_cndmask_b32_e64 v30, v0, v12, s[6:7]
	v_mul_f32_e32 v0, v200, v192
	v_cndmask_b32_e64 v0, v200, v0, s[4:5]
	s_waitcnt lgkmcnt(5)
	v_fma_f32 v2, v14, v186, 0
	v_fma_f32 v4, v15, v187, 0
	v_fmac_f32_e32 v2, v16, v188
	v_fmac_f32_e32 v4, v17, v189
	ds_read_b128 v[186:189], v63 offset:4480
	s_waitcnt lgkmcnt(5)
	v_fmac_f32_e32 v2, v18, v210
	v_fmac_f32_e32 v4, v19, v211
	v_fmac_f32_e32 v2, v20, v212
	v_fmac_f32_e32 v4, v21, v213
	ds_read_b128 v[210:213], v63 offset:4496
	s_waitcnt lgkmcnt(5)
	v_fmac_f32_e32 v2, v22, v194
	v_fmac_f32_e32 v4, v23, v195
	v_fmac_f32_e32 v2, v24, v196
	v_fmac_f32_e32 v4, v25, v197
	ds_read_b128 v[194:197], v63 offset:4512
	s_waitcnt lgkmcnt(5)
	v_fmac_f32_e32 v2, v26, v222
	v_fmac_f32_e32 v4, v27, v223
	v_fmac_f32_e32 v2, v28, v224
	v_fmac_f32_e32 v4, v29, v225
	ds_read_b128 v[222:225], v63 offset:4528
	s_waitcnt lgkmcnt(5)
	v_fmac_f32_e32 v2, v30, v214
	v_add_f32_e32 v2, v4, v2
	s_nop 1
	v_add_f32_dpp v2, v2, v2 quad_perm:[1,0,3,2] row_mask:0xf bank_mask:0xf bound_ctrl:1
	v_fma_f32 v4, v219, v0, -v2
	v_mul_f32_e32 v0, v201, v193
	ds_read_b128 v[190:193], v45 offset:52624
	v_cndmask_b32_e64 v6, v201, v0, s[4:5]
	ds_read_b128 v[198:201], v45 offset:52880
	s_waitcnt lgkmcnt(5)
	v_fma_f32 v7, v14, v186, 0
	v_fma_f32 v8, v15, v187, 0
	v_fmac_f32_e32 v7, v16, v188
	v_fmac_f32_e32 v8, v17, v189
	ds_read_b128 v[186:189], v63 offset:4608
	s_waitcnt lgkmcnt(5)
	v_fmac_f32_e32 v7, v18, v210
	v_fmac_f32_e32 v8, v19, v211
	v_fmac_f32_e32 v7, v20, v212
	v_fmac_f32_e32 v8, v21, v213
	ds_read_b128 v[210:213], v63 offset:4624
	s_waitcnt lgkmcnt(5)
	v_fmac_f32_e32 v7, v22, v194
	v_fmac_f32_e32 v8, v23, v195
	v_fmac_f32_e32 v7, v24, v196
	v_fmac_f32_e32 v8, v25, v197
	ds_read_b128 v[194:197], v63 offset:4640
	s_waitcnt lgkmcnt(5)
	v_fmac_f32_e32 v7, v26, v222
	v_fmac_f32_e32 v7, v28, v224
	v_mul_f32_e32 v0, v4, v203
	ds_read_b128 v[202:205], v63 offset:4656
	v_fmac_f32_e32 v8, v27, v223
	v_fmac_f32_e32 v7, v30, v215
	v_cndmask_b32_e64 v0, 0, v0, s[6:7]
	v_fmac_f32_e32 v8, v29, v225
	v_add_f32_e32 v0, v7, v0
	v_add_f32_e32 v0, v8, v0
	s_nop 1
	v_add_f32_dpp v0, v0, v0 quad_perm:[1,0,3,2] row_mask:0xf bank_mask:0xf bound_ctrl:1
	v_fma_f32 v0, v206, v6, -v0
	v_cndmask_b32_e64 v31, v0, v4, s[6:7]
	ds_read2_b64 v[214:217], v37 offset0:72 offset1:88
	v_add_u32_e32 v218, 0x2600, v62
	ds_read2_b32 v[218:219], v218 offset0:84 offset1:152
	ds_read_b128 v[222:225], v63 offset:4736
	s_waitcnt lgkmcnt(7)
; __device__ void ph_dnpre(const P& p, float* lds) {
;     ...
;       const int c = tid >> 1, par = tid & 1;
;       float xe[32];
;       float* col = c < 64 ? (B2 + c) : (B1 + c - 64);
;       const float* Lp = B0 + par * 2048;
; #pragma unroll
;       for (int i = 0; i < 64; ++i) {
;         float sc = sBeta[i];
;         if (c >= 64) sc *= sEG[i];
;         const float rhs = col[i * LS] * sc;
;         float a0 = 0.f, a1 = 0.f;
; #pragma unroll
;         for (int jj = 0; 2 * jj + 1 < i; ++jj) {
;           const float l = Lp[i * 32 + jj];
;           if (jj & 1) a1 += l * xe[jj]; else a0 += l * xe[jj];
;         }
;         if (i & 1) {
;           const float l = B0[i * 32 + (i >> 1)];
;           a0 += (par == 0) ? l * xe[i >> 1] : 0.f;
;         }
;         float acc = a0 + a1;
;         acc += dpp_f<DPP_XOR1>(acc);
;         const float xi = rhs - acc;
;         if ((i & 1) == 0) xe[i >> 1] = xi;
;         else xe[i >> 1] = (par == 1) ? xi : xe[i >> 1];
;       }
	v_mul_f32_e32 v4, v190, v198
	v_cndmask_b32_e64 v0, v190, v4, s[4:5]
	s_waitcnt lgkmcnt(6)
	v_fma_f32 v4, v14, v186, 0
	v_fma_f32 v12, v15, v187, 0
	v_fmac_f32_e32 v4, v16, v188
	v_fmac_f32_e32 v12, v17, v189
	ds_read2_b32 v[186:187], v36 offset0:178 offset1:243
	s_waitcnt lgkmcnt(6)
	v_fmac_f32_e32 v4, v18, v210
	v_fmac_f32_e32 v12, v19, v211
	v_fmac_f32_e32 v4, v20, v212
	v_fmac_f32_e32 v12, v21, v213
	ds_read_b128 v[210:213], v63 offset:4752
	s_waitcnt lgkmcnt(6)
	v_fmac_f32_e32 v4, v22, v194
	v_fmac_f32_e32 v12, v23, v195
	v_fmac_f32_e32 v4, v24, v196
	v_fmac_f32_e32 v12, v25, v197
	ds_read_b128 v[194:197], v63 offset:4768
	s_waitcnt lgkmcnt(6)
	v_fmac_f32_e32 v4, v26, v202
	v_fmac_f32_e32 v12, v27, v203
	v_fmac_f32_e32 v4, v28, v204
	v_fmac_f32_e32 v12, v29, v205
	ds_read_b128 v[202:205], v63 offset:4784
	s_waitcnt lgkmcnt(6)
	v_fmac_f32_e32 v4, v30, v214
	v_fmac_f32_e32 v12, v31, v215
	v_add_f32_e32 v4, v4, v12
	s_nop 1
	v_add_f32_dpp v4, v4, v4 quad_perm:[1,0,3,2] row_mask:0xf bank_mask:0xf bound_ctrl:1
	v_fma_f32 v0, v207, v0, -v4
	v_mul_f32_e32 v4, v191, v199
	v_cndmask_b32_e64 v1, v191, v4, s[4:5]
	ds_read_b128 v[206:209], v63 offset:4864
	s_waitcnt lgkmcnt(5)
	v_fma_f32 v8, v14, v222, 0
	v_fma_f32 v9, v15, v223, 0
	v_fmac_f32_e32 v8, v16, v224
	v_fmac_f32_e32 v9, v17, v225
	ds_read_b96 v[222:224], v63 offset:4928
	s_waitcnt lgkmcnt(4)
	v_fmac_f32_e32 v8, v18, v210
	v_fmac_f32_e32 v9, v19, v211
	v_fmac_f32_e32 v8, v20, v212
	v_fmac_f32_e32 v9, v21, v213
	ds_read_b128 v[210:213], v63 offset:4880
	s_waitcnt lgkmcnt(4)
	v_fmac_f32_e32 v8, v22, v194
	v_fmac_f32_e32 v9, v23, v195
	v_fmac_f32_e32 v8, v24, v196
	v_fmac_f32_e32 v9, v25, v197
	ds_read_b128 v[194:197], v63 offset:4896
	s_waitcnt lgkmcnt(4)
	v_fmac_f32_e32 v8, v26, v202
	v_fmac_f32_e32 v8, v28, v204
	v_fmac_f32_e32 v9, v27, v203
	v_fmac_f32_e32 v8, v30, v216
	v_mul_f32_e32 v10, v0, v186
	v_fmac_f32_e32 v9, v29, v205
	ds_read_b128 v[202:205], v63 offset:4912
	v_cndmask_b32_e64 v10, 0, v10, s[6:7]
	v_fmac_f32_e32 v9, v31, v217
	v_add_u32_e32 v214, 0x2800, v62
	ds_read2_b32 v[214:215], v214 offset0:92 offset1:160
	v_add_f32_e32 v8, v8, v10
	v_add_f32_e32 v8, v9, v8
	s_nop 1
	v_add_f32_dpp v8, v8, v8 quad_perm:[1,0,3,2] row_mask:0xf bank_mask:0xf bound_ctrl:1
	v_fma_f32 v1, v218, v1, -v8
	v_cndmask_b32_e64 v32, v1, v0, s[6:7]
	v_mul_f32_e32 v0, v192, v200
	v_cndmask_b32_e64 v4, v192, v0, s[4:5]
	s_waitcnt lgkmcnt(5)
	v_fma_f32 v6, v14, v206, 0
	v_fma_f32 v12, v15, v207, 0
	v_fmac_f32_e32 v6, v16, v208
	v_fmac_f32_e32 v12, v17, v209
	ds_read_b128 v[206:209], v63 offset:4992
	s_waitcnt lgkmcnt(4)
	v_fmac_f32_e32 v6, v18, v210
	v_fmac_f32_e32 v12, v19, v211
	v_fmac_f32_e32 v6, v20, v212
	v_fmac_f32_e32 v12, v21, v213
	ds_read_b128 v[210:213], v63 offset:5008
	s_waitcnt lgkmcnt(4)
	v_fmac_f32_e32 v6, v22, v194
	v_fmac_f32_e32 v12, v23, v195
	v_fmac_f32_e32 v6, v24, v196
	v_fmac_f32_e32 v12, v25, v197
	ds_read_b128 v[194:197], v63 offset:5024
	s_waitcnt lgkmcnt(4)
	v_fmac_f32_e32 v6, v26, v202
	v_fmac_f32_e32 v12, v27, v203
	v_fmac_f32_e32 v6, v28, v204
	v_fmac_f32_e32 v12, v29, v205
	ds_read_b128 v[202:205], v63 offset:5040
	v_fmac_f32_e32 v6, v30, v222
	v_fmac_f32_e32 v12, v31, v223
	v_fmac_f32_e32 v6, v32, v224
	ds_read_b96 v[222:224], v63 offset:5056
	v_add_f32_e32 v0, v12, v6
	s_nop 1
	v_add_f32_dpp v0, v0, v0 quad_perm:[1,0,3,2] row_mask:0xf bank_mask:0xf bound_ctrl:1
	v_fma_f32 v4, v219, v4, -v0
	v_mul_f32_e32 v0, v193, v201
	v_cndmask_b32_e64 v5, v193, v0, s[4:5]
	ds_read_b128 v[190:193], v45 offset:52640
	ds_read_b128 v[198:201], v45 offset:52896
	s_waitcnt lgkmcnt(6)
	v_fma_f32 v6, v14, v206, 0
	v_fma_f32 v7, v15, v207, 0
	v_fmac_f32_e32 v6, v16, v208
	v_fmac_f32_e32 v7, v17, v209
	ds_read_b128 v[206:209], v63 offset:5120
	s_waitcnt lgkmcnt(6)
	v_fmac_f32_e32 v6, v18, v210
	v_fmac_f32_e32 v7, v19, v211
	v_fmac_f32_e32 v6, v20, v212
	v_fmac_f32_e32 v7, v21, v213
	ds_read_b128 v[210:213], v63 offset:5136
	s_waitcnt lgkmcnt(6)
	v_fmac_f32_e32 v6, v22, v194
	v_fmac_f32_e32 v7, v23, v195
	v_fmac_f32_e32 v6, v24, v196
	v_fmac_f32_e32 v7, v25, v197
	ds_read_b128 v[194:197], v63 offset:5152
	s_waitcnt lgkmcnt(6)
	v_fmac_f32_e32 v6, v26, v202
	v_fmac_f32_e32 v7, v27, v203
	v_fmac_f32_e32 v6, v28, v204
	v_fmac_f32_e32 v7, v29, v205
	ds_read_b128 v[202:205], v63 offset:5168
	s_waitcnt lgkmcnt(6)
	v_fmac_f32_e32 v6, v30, v222
	v_mul_f32_e32 v0, v4, v187
	v_fmac_f32_e32 v6, v32, v224
	v_cndmask_b32_e64 v0, 0, v0, s[6:7]
	v_fmac_f32_e32 v7, v31, v223
	v_add_f32_e32 v0, v6, v0
	v_add_f32_e32 v0, v7, v0
	s_nop 1
	v_add_f32_dpp v0, v0, v0 quad_perm:[1,0,3,2] row_mask:0xf bank_mask:0xf bound_ctrl:1
	v_fma_f32 v0, v214, v5, -v0
	v_cndmask_b32_e64 v33, v0, v4, s[6:7]
	ds_read_b128 v[186:189], v63 offset:5184
	v_add_u32_e32 v218, 0x2a00, v62
	ds_read2_b32 v[218:219], v218 offset0:100 offset1:168
	ds_read_b128 v[222:225], v63 offset:5248
	s_waitcnt lgkmcnt(7)
	v_mul_f32_e32 v4, v190, v198
	v_cndmask_b32_e64 v0, v190, v4, s[4:5]
	s_waitcnt lgkmcnt(6)
	v_fma_f32 v4, v14, v206, 0
	v_fma_f32 v12, v15, v207, 0
	v_fmac_f32_e32 v4, v16, v208
	v_fmac_f32_e32 v12, v17, v209
	ds_read2_b32 v[206:207], v59 offset0:52 offset1:117
	s_waitcnt lgkmcnt(6)
	v_fmac_f32_e32 v4, v18, v210
	v_fmac_f32_e32 v12, v19, v211
	v_fmac_f32_e32 v4, v20, v212
	v_fmac_f32_e32 v12, v21, v213
	ds_read_b128 v[210:213], v63 offset:5264
	s_waitcnt lgkmcnt(6)
	v_fmac_f32_e32 v4, v22, v194
	v_fmac_f32_e32 v12, v23, v195
	v_fmac_f32_e32 v4, v24, v196
	v_fmac_f32_e32 v12, v25, v197
	ds_read_b128 v[194:197], v63 offset:5280
	s_waitcnt lgkmcnt(6)
; __device__ void ph_dnpre(const P& p, float* lds) {
;     ...
;       const int c = tid >> 1, par = tid & 1;
;       float xe[32];
;       float* col = c < 64 ? (B2 + c) : (B1 + c - 64);
;       const float* Lp = B0 + par * 2048;
; #pragma unroll
;       for (int i = 0; i < 64; ++i) {
;         float sc = sBeta[i];
;         if (c >= 64) sc *= sEG[i];
;         const float rhs = col[i * LS] * sc;
;         float a0 = 0.f, a1 = 0.f;
; #pragma unroll
;         for (int jj = 0; 2 * jj + 1 < i; ++jj) {
;           const float l = Lp[i * 32 + jj];
;           if (jj & 1) a1 += l * xe[jj]; else a0 += l * xe[jj];
;         }
;         if (i & 1) {
;           const float l = B0[i * 32 + (i >> 1)];
;           a0 += (par == 0) ? l * xe[i >> 1] : 0.f;
;         }
;         float acc = a0 + a1;
;         acc += dpp_f<DPP_XOR1>(acc);
;         const float xi = rhs - acc;
;         if ((i & 1) == 0) xe[i >> 1] = xi;
;         else xe[i >> 1] = (par == 1) ? xi : xe[i >> 1];
;       }
	v_fmac_f32_e32 v4, v26, v202
	v_fmac_f32_e32 v12, v27, v203
	v_fmac_f32_e32 v4, v28, v204
	v_fmac_f32_e32 v12, v29, v205
	ds_read_b128 v[202:205], v63 offset:5296
	s_waitcnt lgkmcnt(6)
	v_fmac_f32_e32 v4, v30, v186
	v_fmac_f32_e32 v12, v31, v187
	v_fmac_f32_e32 v4, v32, v188
	v_fmac_f32_e32 v12, v33, v189
	v_add_f32_e32 v4, v4, v12
	s_nop 1
	v_add_f32_dpp v4, v4, v4 quad_perm:[1,0,3,2] row_mask:0xf bank_mask:0xf bound_ctrl:1
	v_fma_f32 v12, v215, v0, -v4
	v_mul_f32_e32 v0, v191, v199
	v_cndmask_b32_e64 v13, v191, v0, s[4:5]
	ds_read_b128 v[186:189], v63 offset:5312
	ds_read_b128 v[214:217], v63 offset:5376
	s_waitcnt lgkmcnt(6)
	v_fma_f32 v34, v14, v222, 0
	v_fma_f32 v35, v15, v223, 0
	v_fmac_f32_e32 v34, v16, v224
	v_fmac_f32_e32 v35, v17, v225
	ds_read_b128 v[222:225], v63 offset:5392
	s_waitcnt lgkmcnt(6)
	v_mul_f32_e32 v4, v12, v206
	v_cndmask_b32_e64 v4, 0, v4, s[6:7]
	s_waitcnt lgkmcnt(5)
	v_fmac_f32_e32 v34, v18, v210
	v_fmac_f32_e32 v35, v19, v211
	v_fmac_f32_e32 v34, v20, v212
	v_fmac_f32_e32 v35, v21, v213
	ds_read_b128 v[210:213], v63 offset:5408
	s_waitcnt lgkmcnt(5)
	v_fmac_f32_e32 v34, v22, v194
	v_fmac_f32_e32 v35, v23, v195
	v_fmac_f32_e32 v34, v24, v196
	v_fmac_f32_e32 v35, v25, v197
	ds_read_b128 v[194:197], v63 offset:5424
	s_waitcnt lgkmcnt(5)
	v_fmac_f32_e32 v34, v26, v202
	v_fmac_f32_e32 v35, v27, v203
	v_fmac_f32_e32 v34, v28, v204
	v_fmac_f32_e32 v35, v29, v205
	ds_read_b128 v[202:205], v63 offset:5440
	s_waitcnt lgkmcnt(5)
	v_fmac_f32_e32 v34, v30, v186
	v_fmac_f32_e32 v35, v31, v187
	v_fmac_f32_e32 v34, v32, v188
	v_fmac_f32_e32 v35, v33, v189
	v_add_f32_e32 v4, v34, v4
	s_nop 0
	v_add_f32_e32 v4, v35, v4
	s_nop 1
	v_add_f32_dpp v4, v4, v4 quad_perm:[1,0,3,2] row_mask:0xf bank_mask:0xf bound_ctrl:1
	v_fma_f32 v0, v218, v13, -v4
	v_cndmask_b32_e64 v34, v0, v12, s[6:7]
	v_mul_f32_e32 v0, v192, v200
	v_cndmask_b32_e64 v0, v192, v0, s[4:5]
	s_waitcnt lgkmcnt(4)
	v_fma_f32 v2, v14, v214, 0
	v_fma_f32 v4, v15, v215, 0
	v_fmac_f32_e32 v2, v16, v216
	v_fmac_f32_e32 v4, v17, v217
	v_add_u32_e32 v6, 0x1400, v63
	ds_read2_b32 v[186:187], v6 offset0:84 offset1:116
	v_add_u32_e32 v214, 0x2c00, v62
	ds_read2_b32 v[214:215], v214 offset0:108 offset1:176
	s_waitcnt lgkmcnt(5)
	v_fmac_f32_e32 v2, v18, v222
	v_fmac_f32_e32 v4, v19, v223
	v_fmac_f32_e32 v2, v20, v224
	v_fmac_f32_e32 v4, v21, v225
	ds_read_b128 v[222:225], v63 offset:5504
	s_waitcnt lgkmcnt(5)
	v_fmac_f32_e32 v2, v22, v210
	v_fmac_f32_e32 v4, v23, v211
	v_fmac_f32_e32 v2, v24, v212
	v_fmac_f32_e32 v4, v25, v213
	ds_read_b128 v[210:213], v63 offset:5520
	s_waitcnt lgkmcnt(5)
	v_fmac_f32_e32 v2, v26, v194
	v_fmac_f32_e32 v4, v27, v195
	v_fmac_f32_e32 v2, v28, v196
	v_fmac_f32_e32 v4, v29, v197
	ds_read_b128 v[194:197], v63 offset:5536
	s_waitcnt lgkmcnt(5)
	v_fmac_f32_e32 v2, v30, v202
	v_fmac_f32_e32 v4, v31, v203
	v_fmac_f32_e32 v2, v32, v204
	v_fmac_f32_e32 v4, v33, v205
	ds_read_b128 v[202:205], v63 offset:5552
	s_waitcnt lgkmcnt(5)
	v_fmac_f32_e32 v2, v34, v186
	v_add_f32_e32 v2, v4, v2
	s_nop 1
	v_add_f32_dpp v2, v2, v2 quad_perm:[1,0,3,2] row_mask:0xf bank_mask:0xf bound_ctrl:1
	v_fma_f32 v4, v219, v0, -v2
	v_mul_f32_e32 v0, v193, v201
	ds_read_b128 v[198:201], v63 offset:5568
	v_cndmask_b32_e64 v6, v193, v0, s[4:5]
	ds_read_b128 v[190:193], v45 offset:52656
	s_waitcnt lgkmcnt(5)
	v_fma_f32 v7, v14, v222, 0
	v_fma_f32 v8, v15, v223, 0
	v_fmac_f32_e32 v7, v16, v224
	v_fmac_f32_e32 v8, v17, v225
	ds_read_b128 v[222:225], v45 offset:52912
	s_waitcnt lgkmcnt(5)
	v_fmac_f32_e32 v7, v18, v210
	v_fmac_f32_e32 v8, v19, v211
	v_fmac_f32_e32 v7, v20, v212
	v_fmac_f32_e32 v8, v21, v213
	ds_read_b128 v[210:213], v63 offset:5632
	s_waitcnt lgkmcnt(5)
	v_fmac_f32_e32 v7, v22, v194
	v_fmac_f32_e32 v8, v23, v195
	v_fmac_f32_e32 v7, v24, v196
	v_fmac_f32_e32 v8, v25, v197
	ds_read_b128 v[194:197], v63 offset:5648
	s_waitcnt lgkmcnt(5)
	v_fmac_f32_e32 v7, v26, v202
	v_fmac_f32_e32 v8, v27, v203
	v_fmac_f32_e32 v7, v28, v204
	v_fmac_f32_e32 v8, v29, v205
	ds_read_b128 v[202:205], v63 offset:5664
	s_waitcnt lgkmcnt(5)
	v_fmac_f32_e32 v7, v30, v198
	v_fmac_f32_e32 v7, v32, v200
	v_mul_f32_e32 v0, v4, v207
	ds_read_b128 v[206:209], v63 offset:5680
	v_fmac_f32_e32 v8, v31, v199
	v_fmac_f32_e32 v7, v34, v187
	v_cndmask_b32_e64 v0, 0, v0, s[6:7]
	v_fmac_f32_e32 v8, v33, v201
	v_add_f32_e32 v0, v7, v0
	v_add_f32_e32 v0, v8, v0
	s_nop 1
	v_add_f32_dpp v0, v0, v0 quad_perm:[1,0,3,2] row_mask:0xf bank_mask:0xf bound_ctrl:1
	v_fma_f32 v0, v214, v6, -v0
	v_cndmask_b32_e64 v35, v0, v4, s[6:7]
	ds_read_b128 v[186:189], v63 offset:5696
	ds_read2_b64 v[198:201], v37 offset0:202 offset1:218
	v_add_u32_e32 v218, 0x2e00, v62
	ds_read2_b32 v[218:219], v218 offset0:116 offset1:184
	s_waitcnt lgkmcnt(7)
	v_mul_f32_e32 v4, v190, v222
	v_cndmask_b32_e64 v0, v190, v4, s[4:5]
	s_waitcnt lgkmcnt(6)
	v_fma_f32 v4, v14, v210, 0
	v_fma_f32 v12, v15, v211, 0
	v_fmac_f32_e32 v4, v16, v212
	v_fmac_f32_e32 v12, v17, v213
	ds_read_b128 v[210:213], v63 offset:5760
	s_waitcnt lgkmcnt(6)
	v_fmac_f32_e32 v4, v18, v194
	v_fmac_f32_e32 v12, v19, v195
	v_fmac_f32_e32 v4, v20, v196
	v_fmac_f32_e32 v12, v21, v197
	ds_read2_b32 v[194:195], v59 offset0:182 offset1:247
	s_waitcnt lgkmcnt(6)
	v_fmac_f32_e32 v4, v22, v202
	v_fmac_f32_e32 v12, v23, v203
	v_fmac_f32_e32 v4, v24, v204
	v_fmac_f32_e32 v12, v25, v205
	ds_read_b128 v[202:205], v63 offset:5776
	s_waitcnt lgkmcnt(6)
	v_fmac_f32_e32 v4, v26, v206
	v_fmac_f32_e32 v12, v27, v207
	v_fmac_f32_e32 v4, v28, v208
	v_fmac_f32_e32 v12, v29, v209
	ds_read_b128 v[206:209], v63 offset:5792
	s_waitcnt lgkmcnt(6)
; __device__ void ph_dnpre(const P& p, float* lds) {
;     ...
;       const int c = tid >> 1, par = tid & 1;
;       float xe[32];
;       float* col = c < 64 ? (B2 + c) : (B1 + c - 64);
;       const float* Lp = B0 + par * 2048;
; #pragma unroll
;       for (int i = 0; i < 64; ++i) {
;         float sc = sBeta[i];
;         if (c >= 64) sc *= sEG[i];
;         const float rhs = col[i * LS] * sc;
;         float a0 = 0.f, a1 = 0.f;
; #pragma unroll
;         for (int jj = 0; 2 * jj + 1 < i; ++jj) {
;           const float l = Lp[i * 32 + jj];
;           if (jj & 1) a1 += l * xe[jj]; else a0 += l * xe[jj];
;         }
;         if (i & 1) {
;           const float l = B0[i * 32 + (i >> 1)];
;           a0 += (par == 0) ? l * xe[i >> 1] : 0.f;
;         }
;         float acc = a0 + a1;
;         acc += dpp_f<DPP_XOR1>(acc);
;         const float xi = rhs - acc;
;         if ((i & 1) == 0) xe[i >> 1] = xi;
;         else xe[i >> 1] = (par == 1) ? xi : xe[i >> 1];
;       }
	v_fmac_f32_e32 v4, v30, v186
	v_fmac_f32_e32 v12, v31, v187
	v_fmac_f32_e32 v4, v32, v188
	v_fmac_f32_e32 v12, v33, v189
	ds_read_b128 v[186:189], v63 offset:5808
	s_waitcnt lgkmcnt(6)
	v_fmac_f32_e32 v4, v34, v198
	v_fmac_f32_e32 v12, v35, v199
	v_add_f32_e32 v4, v4, v12
	s_nop 1
	v_add_f32_dpp v4, v4, v4 quad_perm:[1,0,3,2] row_mask:0xf bank_mask:0xf bound_ctrl:1
	v_fma_f32 v0, v215, v0, -v4
	v_mul_f32_e32 v4, v191, v223
	v_cndmask_b32_e64 v1, v191, v4, s[4:5]
	ds_read_b128 v[214:217], v63 offset:5824
	s_waitcnt lgkmcnt(5)
	v_fma_f32 v8, v14, v210, 0
	v_fma_f32 v9, v15, v211, 0
	v_fmac_f32_e32 v8, v16, v212
	v_fmac_f32_e32 v9, v17, v213
	ds_read_b128 v[210:213], v63 offset:5888
	s_waitcnt lgkmcnt(4)
	v_fmac_f32_e32 v8, v18, v202
	v_fmac_f32_e32 v9, v19, v203
	v_fmac_f32_e32 v8, v20, v204
	v_fmac_f32_e32 v9, v21, v205
	ds_read_b96 v[202:204], v63 offset:5968
	s_waitcnt lgkmcnt(4)
	v_fmac_f32_e32 v8, v22, v206
	v_fmac_f32_e32 v9, v23, v207
	v_fmac_f32_e32 v8, v24, v208
	v_fmac_f32_e32 v9, v25, v209
	ds_read_b128 v[206:209], v63 offset:5904
	s_waitcnt lgkmcnt(4)
	v_fmac_f32_e32 v8, v26, v186
	v_fmac_f32_e32 v9, v27, v187
	v_fmac_f32_e32 v8, v28, v188
	v_fmac_f32_e32 v9, v29, v189
	ds_read_b128 v[186:189], v63 offset:5920
	s_waitcnt lgkmcnt(4)
	v_fmac_f32_e32 v8, v30, v214
	v_fmac_f32_e32 v8, v32, v216
	v_fmac_f32_e32 v9, v31, v215
	v_fmac_f32_e32 v8, v34, v200
	v_mul_f32_e32 v10, v0, v194
	v_fmac_f32_e32 v9, v33, v217
	ds_read_b128 v[214:217], v63 offset:5936
	v_cndmask_b32_e64 v10, 0, v10, s[6:7]
	v_fmac_f32_e32 v9, v35, v201
	ds_read_b128 v[198:201], v63 offset:5952
	v_add_f32_e32 v8, v8, v10
	v_add_f32_e32 v8, v9, v8
	s_nop 1
	v_add_f32_dpp v8, v8, v8 quad_perm:[1,0,3,2] row_mask:0xf bank_mask:0xf bound_ctrl:1
	v_fma_f32 v1, v218, v1, -v8
	v_cndmask_b32_e64 v36, v1, v0, s[6:7]
	v_mul_f32_e32 v0, v192, v224
	v_cndmask_b32_e64 v4, v192, v0, s[4:5]
	s_waitcnt lgkmcnt(5)
	v_fma_f32 v6, v14, v210, 0
	v_fma_f32 v12, v15, v211, 0
	v_fmac_f32_e32 v6, v16, v212
	v_fmac_f32_e32 v12, v17, v213
	v_add_u32_e32 v210, 0x3000, v62
	ds_read2_b32 v[210:211], v210 offset0:124 offset1:192
	s_waitcnt lgkmcnt(4)
	v_fmac_f32_e32 v6, v18, v206
	v_fmac_f32_e32 v12, v19, v207
	v_fmac_f32_e32 v6, v20, v208
	v_fmac_f32_e32 v12, v21, v209
	ds_read_b128 v[206:209], v63 offset:6016
	s_waitcnt lgkmcnt(4)
	v_fmac_f32_e32 v6, v22, v186
	v_fmac_f32_e32 v12, v23, v187
	v_fmac_f32_e32 v6, v24, v188
	v_fmac_f32_e32 v12, v25, v189
	ds_read_b128 v[186:189], v63 offset:6032
	s_waitcnt lgkmcnt(4)
	v_fmac_f32_e32 v6, v26, v214
	v_fmac_f32_e32 v12, v27, v215
	v_fmac_f32_e32 v6, v28, v216
	v_fmac_f32_e32 v12, v29, v217
	ds_read_b128 v[214:217], v63 offset:6048
	s_waitcnt lgkmcnt(4)
	v_fmac_f32_e32 v6, v30, v198
	v_fmac_f32_e32 v12, v31, v199
	v_fmac_f32_e32 v6, v32, v200
	v_fmac_f32_e32 v12, v33, v201
	ds_read_b128 v[198:201], v63 offset:6064
	v_fmac_f32_e32 v6, v34, v202
	v_fmac_f32_e32 v12, v35, v203
	v_fmac_f32_e32 v6, v36, v204
	ds_read_b128 v[202:205], v63 offset:6080
	v_add_f32_e32 v0, v12, v6
	s_nop 1
	v_add_f32_dpp v0, v0, v0 quad_perm:[1,0,3,2] row_mask:0xf bank_mask:0xf bound_ctrl:1
	v_fma_f32 v4, v219, v4, -v0
	v_mul_f32_e32 v0, v193, v225
	v_cndmask_b32_e64 v5, v193, v0, s[4:5]
	ds_read_b96 v[190:192], v63 offset:6096
	ds_read_b128 v[222:225], v45 offset:52672
	s_waitcnt lgkmcnt(6)
	v_fma_f32 v6, v14, v206, 0
	v_fma_f32 v7, v15, v207, 0
	v_fmac_f32_e32 v6, v16, v208
	v_fmac_f32_e32 v7, v17, v209
	ds_read_b128 v[206:209], v45 offset:52928
	s_waitcnt lgkmcnt(6)
	v_fmac_f32_e32 v6, v18, v186
	v_fmac_f32_e32 v7, v19, v187
	v_fmac_f32_e32 v6, v20, v188
	v_fmac_f32_e32 v7, v21, v189
	ds_read_b128 v[186:189], v63 offset:6144
	s_waitcnt lgkmcnt(6)
	v_fmac_f32_e32 v6, v22, v214
	v_fmac_f32_e32 v7, v23, v215
	v_fmac_f32_e32 v6, v24, v216
	v_fmac_f32_e32 v7, v25, v217
	ds_read_b128 v[214:217], v63 offset:6160
	s_waitcnt lgkmcnt(6)
	v_fmac_f32_e32 v6, v26, v198
	v_fmac_f32_e32 v7, v27, v199
	v_fmac_f32_e32 v6, v28, v200
	v_fmac_f32_e32 v7, v29, v201
	ds_read_b128 v[198:201], v63 offset:6176
	s_waitcnt lgkmcnt(6)
	v_fmac_f32_e32 v6, v30, v202
	v_fmac_f32_e32 v7, v31, v203
	v_fmac_f32_e32 v6, v32, v204
	v_fmac_f32_e32 v7, v33, v205
	ds_read_b128 v[202:205], v63 offset:6192
	s_waitcnt lgkmcnt(6)
	v_fmac_f32_e32 v6, v34, v190
	v_mul_f32_e32 v0, v4, v195
	v_fmac_f32_e32 v6, v36, v192
	v_cndmask_b32_e64 v0, 0, v0, s[6:7]
	v_fmac_f32_e32 v7, v35, v191
	v_add_f32_e32 v0, v6, v0
	v_add_f32_e32 v0, v7, v0
	s_nop 1
	v_add_f32_dpp v0, v0, v0 quad_perm:[1,0,3,2] row_mask:0xf bank_mask:0xf bound_ctrl:1
	v_fma_f32 v0, v210, v5, -v0
	v_cndmask_b32_e64 v37, v0, v4, s[6:7]
	ds_read_b128 v[190:193], v63 offset:6208
	ds_read_b128 v[194:197], v63 offset:6224
	s_waitcnt lgkmcnt(6)
	v_mul_f32_e32 v4, v222, v206
	v_cndmask_b32_e64 v0, v222, v4, s[4:5]
	s_waitcnt lgkmcnt(5)
	v_fma_f32 v4, v14, v186, 0
	v_fma_f32 v12, v15, v187, 0
	v_fmac_f32_e32 v4, v16, v188
	v_fmac_f32_e32 v12, v17, v189
	s_waitcnt lgkmcnt(4)
	v_fmac_f32_e32 v4, v18, v214
	v_fmac_f32_e32 v12, v19, v215
	v_fmac_f32_e32 v4, v20, v216
	v_fmac_f32_e32 v12, v21, v217
	s_waitcnt lgkmcnt(3)
	v_fmac_f32_e32 v4, v22, v198
	v_fmac_f32_e32 v12, v23, v199
	v_fmac_f32_e32 v4, v24, v200
	v_fmac_f32_e32 v12, v25, v201
	s_waitcnt lgkmcnt(2)
	v_fmac_f32_e32 v4, v26, v202
	v_fmac_f32_e32 v12, v27, v203
	v_fmac_f32_e32 v4, v28, v204
	v_fmac_f32_e32 v12, v29, v205
	s_waitcnt lgkmcnt(1)
	v_fmac_f32_e32 v4, v30, v190
	v_fmac_f32_e32 v12, v31, v191
	v_fmac_f32_e32 v4, v32, v192
	v_fmac_f32_e32 v12, v33, v193
	s_waitcnt lgkmcnt(0)
; __device__ void ph_dnpre(const P& p, float* lds) {
;     ...
;       const int c = tid >> 1, par = tid & 1;
;       float xe[32];
;       float* col = c < 64 ? (B2 + c) : (B1 + c - 64);
;       const float* Lp = B0 + par * 2048;
; #pragma unroll
;       for (int i = 0; i < 64; ++i) {
;         float sc = sBeta[i];
;         if (c >= 64) sc *= sEG[i];
;         const float rhs = col[i * LS] * sc;
;         float a0 = 0.f, a1 = 0.f;
; #pragma unroll
;         for (int jj = 0; 2 * jj + 1 < i; ++jj) {
;           const float l = Lp[i * 32 + jj];
;           if (jj & 1) a1 += l * xe[jj]; else a0 += l * xe[jj];
;         }
;         if (i & 1) {
;           const float l = B0[i * 32 + (i >> 1)];
;           a0 += (par == 0) ? l * xe[i >> 1] : 0.f;
;         }
;         float acc = a0 + a1;
;         acc += dpp_f<DPP_XOR1>(acc);
;         const float xi = rhs - acc;
;         if ((i & 1) == 0) xe[i >> 1] = xi;
;         else xe[i >> 1] = (par == 1) ? xi : xe[i >> 1];
;       }
	v_fmac_f32_e32 v4, v34, v194
	v_fmac_f32_e32 v12, v35, v195
	v_fmac_f32_e32 v4, v36, v196
	v_fmac_f32_e32 v12, v37, v197
	v_add_f32_e32 v4, v4, v12
	s_nop 1
	v_add_f32_dpp v4, v4, v4 quad_perm:[1,0,3,2] row_mask:0xf bank_mask:0xf bound_ctrl:1
	v_fma_f32 v12, v211, v0, -v4
	v_mul_f32_e32 v0, v223, v207
	v_add_u32_e32 v39, 0x3400, v62
	ds_read2_b32 v[218:219], v39 offset0:4 offset1:72
	ds_read_b128 v[186:189], v63 offset:6272
	ds_read2_b32 v[190:191], v151 offset0:56 offset1:121
	ds_read_b128 v[194:197], v63 offset:6288
	ds_read_b128 v[198:201], v63 offset:6304
	ds_read_b128 v[202:205], v63 offset:6320
	v_cndmask_b32_e64 v13, v223, v0, s[4:5]
	ds_read_b128 v[210:213], v63 offset:6336
	ds_read_b128 v[214:217], v63 offset:6352
	s_waitcnt lgkmcnt(6)
	v_fma_f32 v38, v14, v186, 0
	v_fma_f32 v59, v15, v187, 0
	v_fmac_f32_e32 v38, v16, v188
	v_fmac_f32_e32 v59, v17, v189
	ds_read_b128 v[186:189], v63 offset:6400
	s_waitcnt lgkmcnt(6)
	v_mul_f32_e32 v4, v12, v190
	v_cndmask_b32_e64 v4, 0, v4, s[6:7]
	s_waitcnt lgkmcnt(5)
	v_fmac_f32_e32 v38, v18, v194
	v_fmac_f32_e32 v59, v19, v195
	v_fmac_f32_e32 v38, v20, v196
	v_fmac_f32_e32 v59, v21, v197
	ds_read_b128 v[194:197], v63 offset:6416
	s_waitcnt lgkmcnt(5)
	v_fmac_f32_e32 v38, v22, v198
	v_fmac_f32_e32 v59, v23, v199
	v_fmac_f32_e32 v38, v24, v200
	v_fmac_f32_e32 v59, v25, v201
	ds_read_b128 v[198:201], v63 offset:6432
	s_waitcnt lgkmcnt(5)
	v_fmac_f32_e32 v38, v26, v202
	v_fmac_f32_e32 v59, v27, v203
	v_fmac_f32_e32 v38, v28, v204
	v_fmac_f32_e32 v59, v29, v205
	ds_read_b128 v[202:205], v63 offset:6448
	s_waitcnt lgkmcnt(5)
	v_fmac_f32_e32 v38, v30, v210
	v_fmac_f32_e32 v59, v31, v211
	v_fmac_f32_e32 v38, v32, v212
	v_fmac_f32_e32 v59, v33, v213
	ds_read_b128 v[210:213], v63 offset:6464
	s_waitcnt lgkmcnt(5)
	v_fmac_f32_e32 v38, v34, v214
	v_fmac_f32_e32 v59, v35, v215
	v_fmac_f32_e32 v38, v36, v216
	v_fmac_f32_e32 v59, v37, v217
	ds_read_b128 v[214:217], v63 offset:6480
	v_add_f32_e32 v4, v38, v4
	s_nop 0
	v_add_f32_e32 v4, v59, v4
	s_nop 1
	v_add_f32_dpp v4, v4, v4 quad_perm:[1,0,3,2] row_mask:0xf bank_mask:0xf bound_ctrl:1
	v_fma_f32 v0, v218, v13, -v4
	v_cndmask_b32_e64 v38, v0, v12, s[6:7]
	v_mul_f32_e32 v0, v224, v208
	v_cndmask_b32_e64 v0, v224, v0, s[4:5]
	s_waitcnt lgkmcnt(5)
	v_fma_f32 v2, v14, v186, 0
	v_fma_f32 v4, v15, v187, 0
	v_fmac_f32_e32 v2, v16, v188
	v_fmac_f32_e32 v4, v17, v189
	s_waitcnt lgkmcnt(4)
	v_fmac_f32_e32 v2, v18, v194
	v_fmac_f32_e32 v4, v19, v195
	v_fmac_f32_e32 v2, v20, v196
	v_fmac_f32_e32 v4, v21, v197
	s_waitcnt lgkmcnt(3)
	v_fmac_f32_e32 v2, v22, v198
	v_fmac_f32_e32 v4, v23, v199
	v_fmac_f32_e32 v2, v24, v200
	v_fmac_f32_e32 v4, v25, v201
	s_waitcnt lgkmcnt(2)
	v_fmac_f32_e32 v2, v26, v202
	v_fmac_f32_e32 v4, v27, v203
	v_fmac_f32_e32 v2, v28, v204
	v_fmac_f32_e32 v4, v29, v205
	s_waitcnt lgkmcnt(1)
	v_fmac_f32_e32 v2, v30, v210
	v_fmac_f32_e32 v4, v31, v211
	v_fmac_f32_e32 v2, v32, v212
	v_fmac_f32_e32 v4, v33, v213
	s_waitcnt lgkmcnt(0)
	v_fmac_f32_e32 v2, v34, v214
	v_fmac_f32_e32 v4, v35, v215
	v_add_u32_e32 v8, 0x1800, v63
	ds_read2_b32 v[186:187], v8 offset0:88 offset1:120
	ds_read2_b32 v[194:195], v39 offset0:140 offset1:208
	ds_read_b128 v[198:201], v63 offset:6528
	ds_read_b128 v[202:205], v63 offset:6544
	ds_read_b128 v[210:213], v63 offset:6560
	v_fmac_f32_e32 v2, v36, v216
	v_fmac_f32_e32 v4, v37, v217
	ds_read_b128 v[214:217], v63 offset:6576
	s_waitcnt lgkmcnt(5)
	v_fmac_f32_e32 v2, v38, v186
	v_add_f32_e32 v2, v4, v2
	s_nop 1
	v_add_f32_dpp v2, v2, v2 quad_perm:[1,0,3,2] row_mask:0xf bank_mask:0xf bound_ctrl:1
	v_fma_f32 v4, v219, v0, -v2
	v_mul_f32_e32 v0, v225, v209
	ds_read_b128 v[206:209], v63 offset:6592
	v_cndmask_b32_e64 v6, v225, v0, s[4:5]
	ds_read_b128 v[222:225], v63 offset:6608
	s_waitcnt lgkmcnt(5)
	v_fma_f32 v7, v14, v198, 0
	v_fma_f32 v9, v15, v199, 0
	v_fmac_f32_e32 v7, v16, v200
	v_fmac_f32_e32 v9, v17, v201
	ds_read_b128 v[198:201], v45 offset:52688
	s_waitcnt lgkmcnt(5)
	v_fmac_f32_e32 v7, v18, v202
	v_fmac_f32_e32 v9, v19, v203
	v_fmac_f32_e32 v7, v20, v204
	v_fmac_f32_e32 v9, v21, v205
	ds_read_b128 v[202:205], v45 offset:52944
	s_waitcnt lgkmcnt(5)
	v_fmac_f32_e32 v7, v22, v210
	v_fmac_f32_e32 v9, v23, v211
	v_fmac_f32_e32 v7, v24, v212
	v_fmac_f32_e32 v9, v25, v213
	ds_read_b128 v[210:213], v63 offset:6656
	s_waitcnt lgkmcnt(5)
	v_fmac_f32_e32 v7, v26, v214
	v_fmac_f32_e32 v9, v27, v215
	v_fmac_f32_e32 v7, v28, v216
	v_fmac_f32_e32 v9, v29, v217
	ds_read_b128 v[214:217], v63 offset:6672
	s_waitcnt lgkmcnt(5)
	v_fmac_f32_e32 v7, v30, v206
	v_fmac_f32_e32 v9, v31, v207
	v_fmac_f32_e32 v7, v32, v208
	v_fmac_f32_e32 v9, v33, v209
	ds_read_b128 v[206:209], v63 offset:6688
	s_waitcnt lgkmcnt(5)
	v_fmac_f32_e32 v7, v34, v222
	v_fmac_f32_e32 v7, v36, v224
	v_mul_f32_e32 v0, v4, v191
	ds_read_b128 v[190:193], v63 offset:6704
	v_fmac_f32_e32 v9, v35, v223
	v_fmac_f32_e32 v7, v38, v187
	v_cndmask_b32_e64 v0, 0, v0, s[6:7]
	v_fmac_f32_e32 v9, v37, v225
	v_add_f32_e32 v0, v7, v0
	v_add_f32_e32 v0, v9, v0
	s_nop 1
	v_add_f32_dpp v0, v0, v0 quad_perm:[1,0,3,2] row_mask:0xf bank_mask:0xf bound_ctrl:1
	v_fma_f32 v0, v194, v6, -v0
	v_cndmask_b32_e64 v39, v0, v4, s[6:7]
	ds_read_b128 v[186:189], v63 offset:6720
	ds_read_b128 v[222:225], v63 offset:6736
	s_waitcnt lgkmcnt(6)
	v_mul_f32_e32 v4, v198, v202
	v_cndmask_b32_e64 v0, v198, v4, s[4:5]
	s_waitcnt lgkmcnt(5)
	v_fma_f32 v4, v14, v210, 0
	v_fma_f32 v9, v15, v211, 0
	v_fmac_f32_e32 v4, v16, v212
	v_fmac_f32_e32 v9, v17, v213
	ds_read2_b64 v[210:213], v8 offset0:76 offset1:92
	s_waitcnt lgkmcnt(5)
	v_fmac_f32_e32 v4, v18, v214
	v_fmac_f32_e32 v9, v19, v215
	v_fmac_f32_e32 v4, v20, v216
	v_fmac_f32_e32 v9, v21, v217
	s_waitcnt lgkmcnt(4)
; __device__ void ph_dnpre(const P& p, float* lds) {
;     ...
;       const int c = tid >> 1, par = tid & 1;
;       float xe[32];
;       float* col = c < 64 ? (B2 + c) : (B1 + c - 64);
;       const float* Lp = B0 + par * 2048;
; #pragma unroll
;       for (int i = 0; i < 64; ++i) {
;         float sc = sBeta[i];
;         if (c >= 64) sc *= sEG[i];
;         const float rhs = col[i * LS] * sc;
;         float a0 = 0.f, a1 = 0.f;
; #pragma unroll
;         for (int jj = 0; 2 * jj + 1 < i; ++jj) {
;           const float l = Lp[i * 32 + jj];
;           if (jj & 1) a1 += l * xe[jj]; else a0 += l * xe[jj];
;         }
;         if (i & 1) {
;           const float l = B0[i * 32 + (i >> 1)];
;           a0 += (par == 0) ? l * xe[i >> 1] : 0.f;
;         }
;         float acc = a0 + a1;
;         acc += dpp_f<DPP_XOR1>(acc);
;         const float xi = rhs - acc;
;         if ((i & 1) == 0) xe[i >> 1] = xi;
;         else xe[i >> 1] = (par == 1) ? xi : xe[i >> 1];
;       }
	v_fmac_f32_e32 v4, v22, v206
	v_fmac_f32_e32 v9, v23, v207
	v_fmac_f32_e32 v4, v24, v208
	v_fmac_f32_e32 v9, v25, v209
	s_waitcnt lgkmcnt(3)
	v_fmac_f32_e32 v4, v26, v190
	v_fmac_f32_e32 v9, v27, v191
	v_fmac_f32_e32 v4, v28, v192
	v_fmac_f32_e32 v9, v29, v193
	s_waitcnt lgkmcnt(2)
	v_fmac_f32_e32 v4, v30, v186
	v_fmac_f32_e32 v9, v31, v187
	v_fmac_f32_e32 v4, v32, v188
	v_fmac_f32_e32 v9, v33, v189
	s_waitcnt lgkmcnt(1)
	v_fmac_f32_e32 v4, v34, v222
	v_fmac_f32_e32 v9, v35, v223
	v_fmac_f32_e32 v4, v36, v224
	v_fmac_f32_e32 v9, v37, v225
	s_waitcnt lgkmcnt(0)
	v_fmac_f32_e32 v4, v38, v210
	v_fmac_f32_e32 v9, v39, v211
	v_add_f32_e32 v4, v4, v9
	v_add_u32_e32 v9, 0x3800, v62
	ds_read2_b32 v[218:219], v9 offset0:20 offset1:88
	ds_read_b128 v[186:189], v63 offset:6784
	ds_read_b128 v[190:193], v63 offset:6800
	ds_read_b128 v[206:209], v63 offset:6816
	ds_read_b128 v[214:217], v63 offset:6832
	ds_read_b128 v[222:225], v63 offset:6848
	s_nop 0
	v_add_f32_dpp v4, v4, v4 quad_perm:[1,0,3,2] row_mask:0xf bank_mask:0xf bound_ctrl:1
	v_fma_f32 v0, v195, v0, -v4
	v_mul_f32_e32 v4, v199, v203
	v_cndmask_b32_e64 v1, v199, v4, s[4:5]
	ds_read_b128 v[194:197], v63 offset:6864
	s_waitcnt lgkmcnt(5)
	v_fma_f32 v10, v14, v186, 0
	v_fma_f32 v11, v15, v187, 0
	v_fmac_f32_e32 v10, v16, v188
	v_fmac_f32_e32 v11, v17, v189
	ds_read2_b32 v[186:187], v151 offset0:186 offset1:251
	s_waitcnt lgkmcnt(5)
	v_fmac_f32_e32 v10, v18, v190
	v_fmac_f32_e32 v11, v19, v191
	v_fmac_f32_e32 v10, v20, v192
	v_fmac_f32_e32 v11, v21, v193
	ds_read_b128 v[190:193], v63 offset:6912
	s_waitcnt lgkmcnt(5)
	v_fmac_f32_e32 v10, v22, v206
	v_fmac_f32_e32 v11, v23, v207
	v_fmac_f32_e32 v10, v24, v208
	v_fmac_f32_e32 v11, v25, v209
	ds_read_b96 v[206:208], v63 offset:7008
	s_waitcnt lgkmcnt(5)
	v_fmac_f32_e32 v10, v26, v214
	v_fmac_f32_e32 v11, v27, v215
	v_fmac_f32_e32 v10, v28, v216
	v_fmac_f32_e32 v11, v29, v217
	ds_read_b128 v[214:217], v63 offset:6928
	s_waitcnt lgkmcnt(5)
	v_fmac_f32_e32 v10, v30, v222
	v_fmac_f32_e32 v11, v31, v223
	v_fmac_f32_e32 v10, v32, v224
	v_fmac_f32_e32 v11, v33, v225
	ds_read_b128 v[222:225], v63 offset:6944
	s_waitcnt lgkmcnt(5)
	v_fmac_f32_e32 v10, v34, v194
	v_fmac_f32_e32 v11, v35, v195
	v_fmac_f32_e32 v10, v36, v196
	v_fmac_f32_e32 v10, v38, v212
	v_fmac_f32_e32 v11, v37, v197
	ds_read_b128 v[194:197], v63 offset:6960
	v_fmac_f32_e32 v11, v39, v213
	ds_read_b128 v[210:213], v63 offset:6976
	s_waitcnt lgkmcnt(6)
	v_mul_f32_e32 v12, v0, v186
	v_cndmask_b32_e64 v12, 0, v12, s[6:7]
	v_add_f32_e32 v10, v10, v12
	v_add_f32_e32 v10, v11, v10
	s_nop 1
	v_add_f32_dpp v10, v10, v10 quad_perm:[1,0,3,2] row_mask:0xf bank_mask:0xf bound_ctrl:1
	v_fma_f32 v1, v218, v1, -v10
	v_cndmask_b32_e64 v59, v1, v0, s[6:7]
	v_mul_f32_e32 v0, v200, v204
	v_cndmask_b32_e64 v4, v200, v0, s[4:5]
	s_waitcnt lgkmcnt(5)
	v_fma_f32 v6, v14, v190, 0
	v_fma_f32 v151, v15, v191, 0
	v_fmac_f32_e32 v6, v16, v192
	v_fmac_f32_e32 v151, v17, v193
	ds_read_b128 v[190:193], v63 offset:6992
	s_waitcnt lgkmcnt(4)
	v_fmac_f32_e32 v6, v18, v214
	v_fmac_f32_e32 v151, v19, v215
	v_fmac_f32_e32 v6, v20, v216
	v_fmac_f32_e32 v151, v21, v217
	ds_read2_b32 v[214:215], v9 offset0:156 offset1:224
	s_waitcnt lgkmcnt(4)
	v_fmac_f32_e32 v6, v22, v222
	v_fmac_f32_e32 v151, v23, v223
	v_fmac_f32_e32 v6, v24, v224
	v_fmac_f32_e32 v151, v25, v225
	ds_read_b128 v[222:225], v63 offset:7040
	s_waitcnt lgkmcnt(4)
	v_fmac_f32_e32 v6, v26, v194
	v_fmac_f32_e32 v151, v27, v195
	v_fmac_f32_e32 v6, v28, v196
	v_fmac_f32_e32 v151, v29, v197
	ds_read_b128 v[194:197], v63 offset:7056
	s_waitcnt lgkmcnt(4)
	v_fmac_f32_e32 v6, v30, v210
	v_fmac_f32_e32 v151, v31, v211
	v_fmac_f32_e32 v6, v32, v212
	v_fmac_f32_e32 v151, v33, v213
	ds_read_b128 v[210:213], v63 offset:7072
	s_waitcnt lgkmcnt(4)
	v_fmac_f32_e32 v6, v34, v190
	v_fmac_f32_e32 v151, v35, v191
	v_fmac_f32_e32 v6, v36, v192
	v_fmac_f32_e32 v151, v37, v193
	ds_read_b128 v[190:193], v63 offset:7088
	v_fmac_f32_e32 v6, v38, v206
	v_fmac_f32_e32 v151, v39, v207
	v_fmac_f32_e32 v6, v59, v208
	ds_read_b128 v[206:209], v63 offset:7104
	v_add_f32_e32 v0, v151, v6
	s_nop 1
	v_add_f32_dpp v0, v0, v0 quad_perm:[1,0,3,2] row_mask:0xf bank_mask:0xf bound_ctrl:1
	v_fma_f32 v4, v219, v4, -v0
	v_mul_f32_e32 v0, v201, v205
	v_cndmask_b32_e64 v5, v201, v0, s[4:5]
	ds_read_b128 v[198:201], v63 offset:7120
	ds_read_b96 v[202:204], v63 offset:7136
	s_waitcnt lgkmcnt(6)
	v_fma_f32 v6, v14, v222, 0
	v_fma_f32 v7, v15, v223, 0
	v_fmac_f32_e32 v6, v16, v224
	v_fmac_f32_e32 v7, v17, v225
	ds_read_b128 v[222:225], v45 offset:52704
	s_waitcnt lgkmcnt(6)
	v_fmac_f32_e32 v6, v18, v194
	v_fmac_f32_e32 v7, v19, v195
	v_fmac_f32_e32 v6, v20, v196
	v_fmac_f32_e32 v7, v21, v197
	ds_read_b128 v[194:197], v45 offset:52960
	s_waitcnt lgkmcnt(6)
	v_fmac_f32_e32 v6, v22, v210
	v_fmac_f32_e32 v7, v23, v211
	v_fmac_f32_e32 v6, v24, v212
	v_fmac_f32_e32 v7, v25, v213
	ds_read_b128 v[210:213], v63 offset:7168
	s_waitcnt lgkmcnt(6)
	v_fmac_f32_e32 v6, v26, v190
	v_fmac_f32_e32 v7, v27, v191
	v_fmac_f32_e32 v6, v28, v192
	v_fmac_f32_e32 v7, v29, v193
	ds_read_b128 v[190:193], v63 offset:7184
	s_waitcnt lgkmcnt(6)
	v_fmac_f32_e32 v6, v30, v206
	v_fmac_f32_e32 v7, v31, v207
	v_fmac_f32_e32 v6, v32, v208
	v_fmac_f32_e32 v7, v33, v209
	ds_read_b128 v[206:209], v63 offset:7200
	s_waitcnt lgkmcnt(6)
	v_fmac_f32_e32 v6, v34, v198
	v_fmac_f32_e32 v7, v35, v199
	v_fmac_f32_e32 v6, v36, v200
	v_fmac_f32_e32 v7, v37, v201
	ds_read_b128 v[198:201], v63 offset:7216
	s_waitcnt lgkmcnt(6)
; __device__ void ph_dnpre(const P& p, float* lds) {
;     ...
;       const int c = tid >> 1, par = tid & 1;
;       float xe[32];
;       float* col = c < 64 ? (B2 + c) : (B1 + c - 64);
;       const float* Lp = B0 + par * 2048;
; #pragma unroll
;       for (int i = 0; i < 64; ++i) {
;         float sc = sBeta[i];
;         if (c >= 64) sc *= sEG[i];
;         const float rhs = col[i * LS] * sc;
;         float a0 = 0.f, a1 = 0.f;
; #pragma unroll
;         for (int jj = 0; 2 * jj + 1 < i; ++jj) {
;           const float l = Lp[i * 32 + jj];
;           if (jj & 1) a1 += l * xe[jj]; else a0 += l * xe[jj];
;         }
;         if (i & 1) {
;           const float l = B0[i * 32 + (i >> 1)];
;           a0 += (par == 0) ? l * xe[i >> 1] : 0.f;
;         }
;         float acc = a0 + a1;
;         acc += dpp_f<DPP_XOR1>(acc);
;         const float xi = rhs - acc;
;         if ((i & 1) == 0) xe[i >> 1] = xi;
;         else xe[i >> 1] = (par == 1) ? xi : xe[i >> 1];
;       }
	v_fmac_f32_e32 v6, v38, v202
	v_mul_f32_e32 v0, v4, v187
	v_fmac_f32_e32 v6, v59, v204
	v_cndmask_b32_e64 v0, 0, v0, s[6:7]
	v_fmac_f32_e32 v7, v39, v203
	v_add_f32_e32 v0, v6, v0
	v_add_f32_e32 v0, v7, v0
	v_add_u32_e64 v153, s10, 0
	s_lshl_b64 s[10:11], s[2:3], 14
	v_add_f32_dpp v0, v0, v0 quad_perm:[1,0,3,2] row_mask:0xf bank_mask:0xf bound_ctrl:1
	v_fma_f32 v0, v214, v5, -v0
	v_cndmask_b32_e64 v151, v0, v4, s[6:7]
	ds_read_b128 v[186:189], v63 offset:7232
	ds_read_b128 v[202:205], v63 offset:7248
	v_add_u32_e32 v154, 0x3c00, v62
	s_waitcnt lgkmcnt(6)
	v_mul_f32_e32 v4, v222, v194
	v_cndmask_b32_e64 v0, v222, v4, s[4:5]
	s_waitcnt lgkmcnt(5)
	v_fma_f32 v4, v14, v210, 0
	v_fma_f32 v9, v15, v211, 0
	v_fmac_f32_e32 v4, v16, v212
	v_fmac_f32_e32 v9, v17, v213
	ds_read_b128 v[210:213], v63 offset:7264
	ds_read2_b32 v[218:219], v154 offset0:36 offset1:104
	s_waitcnt lgkmcnt(6)
	v_fmac_f32_e32 v4, v18, v190
	v_fmac_f32_e32 v9, v19, v191
	v_fmac_f32_e32 v4, v20, v192
	v_fmac_f32_e32 v9, v21, v193
	ds_read_b128 v[190:193], v63 offset:7296
	s_waitcnt lgkmcnt(6)
	v_fmac_f32_e32 v4, v22, v206
	v_fmac_f32_e32 v9, v23, v207
	v_fmac_f32_e32 v4, v24, v208
	v_fmac_f32_e32 v9, v25, v209
	ds_read2_b32 v[206:207], v153 offset0:60 offset1:125
	s_waitcnt lgkmcnt(6)
	v_fmac_f32_e32 v4, v26, v198
	v_fmac_f32_e32 v9, v27, v199
	v_fmac_f32_e32 v4, v28, v200
	v_fmac_f32_e32 v9, v29, v201
	ds_read_b128 v[198:201], v63 offset:7312
	s_waitcnt lgkmcnt(6)
	v_fmac_f32_e32 v4, v30, v186
	v_fmac_f32_e32 v9, v31, v187
	v_fmac_f32_e32 v4, v32, v188
	v_fmac_f32_e32 v9, v33, v189
	ds_read_b128 v[186:189], v63 offset:7328
	s_waitcnt lgkmcnt(6)
	v_fmac_f32_e32 v4, v34, v202
	v_fmac_f32_e32 v9, v35, v203
	v_fmac_f32_e32 v4, v36, v204
	v_fmac_f32_e32 v9, v37, v205
	ds_read_b128 v[202:205], v63 offset:7344
	s_waitcnt lgkmcnt(6)
	v_fmac_f32_e32 v4, v38, v210
	v_fmac_f32_e32 v9, v39, v211
	v_fmac_f32_e32 v4, v59, v212
	v_fmac_f32_e32 v9, v151, v213
	v_add_f32_e32 v4, v4, v9
	s_nop 1
	v_add_f32_dpp v4, v4, v4 quad_perm:[1,0,3,2] row_mask:0xf bank_mask:0xf bound_ctrl:1
	v_fma_f32 v9, v215, v0, -v4
	v_mul_f32_e32 v0, v223, v195
	v_cndmask_b32_e64 v152, v223, v0, s[4:5]
	ds_read_b128 v[210:213], v63 offset:7360
	ds_read_b128 v[214:217], v63 offset:7376
	s_waitcnt lgkmcnt(6)
	v_fma_f32 v155, v14, v190, 0
	v_fma_f32 v156, v15, v191, 0
	v_fmac_f32_e32 v155, v16, v192
	v_fmac_f32_e32 v156, v17, v193
	ds_read_b128 v[190:193], v63 offset:7392
	s_waitcnt lgkmcnt(6)
	v_mul_f32_e32 v4, v9, v206
	v_cndmask_b32_e64 v4, 0, v4, s[6:7]
	s_waitcnt lgkmcnt(5)
	v_fmac_f32_e32 v155, v18, v198
	v_fmac_f32_e32 v156, v19, v199
	v_fmac_f32_e32 v155, v20, v200
	v_fmac_f32_e32 v156, v21, v201
	ds_read_b128 v[198:201], v63 offset:7424
	s_waitcnt lgkmcnt(5)
	v_fmac_f32_e32 v155, v22, v186
	v_fmac_f32_e32 v156, v23, v187
	v_fmac_f32_e32 v155, v24, v188
	v_fmac_f32_e32 v156, v25, v189
	ds_read_b128 v[186:189], v63 offset:7440
	s_waitcnt lgkmcnt(5)
	v_fmac_f32_e32 v155, v26, v202
	v_fmac_f32_e32 v156, v27, v203
	v_fmac_f32_e32 v155, v28, v204
	v_fmac_f32_e32 v156, v29, v205
	ds_read_b128 v[202:205], v63 offset:7456
	s_waitcnt lgkmcnt(5)
	v_fmac_f32_e32 v155, v30, v210
	v_fmac_f32_e32 v156, v31, v211
	v_fmac_f32_e32 v155, v32, v212
	v_fmac_f32_e32 v156, v33, v213
	ds_read_b128 v[210:213], v63 offset:7472
	s_waitcnt lgkmcnt(5)
	v_fmac_f32_e32 v155, v34, v214
	v_fmac_f32_e32 v156, v35, v215
	v_fmac_f32_e32 v155, v36, v216
	v_fmac_f32_e32 v156, v37, v217
	ds_read_b128 v[214:217], v63 offset:7488
	s_waitcnt lgkmcnt(5)
	v_fmac_f32_e32 v155, v38, v190
	v_fmac_f32_e32 v156, v39, v191
	v_fmac_f32_e32 v155, v59, v192
	v_fmac_f32_e32 v156, v151, v193
	ds_read_b128 v[190:193], v63 offset:7504
	v_add_f32_e32 v4, v155, v4
	s_nop 0
	v_add_f32_e32 v4, v156, v4
	s_nop 1
	v_add_f32_dpp v4, v4, v4 quad_perm:[1,0,3,2] row_mask:0xf bank_mask:0xf bound_ctrl:1
	v_fma_f32 v0, v218, v152, -v4
	v_cndmask_b32_e64 v152, v0, v9, s[6:7]
	v_mul_f32_e32 v0, v224, v196
	v_cndmask_b32_e64 v0, v224, v0, s[4:5]
	s_waitcnt lgkmcnt(5)
	v_fma_f32 v2, v14, v198, 0
	v_fma_f32 v4, v15, v199, 0
	v_fmac_f32_e32 v2, v16, v200
	v_fmac_f32_e32 v4, v17, v201
	ds_read_b128 v[198:201], v63 offset:7520
	v_add_u32_e32 v6, 0x1c00, v63
	s_waitcnt lgkmcnt(5)
	v_fmac_f32_e32 v2, v18, v186
	v_fmac_f32_e32 v4, v19, v187
	v_fmac_f32_e32 v2, v20, v188
	v_fmac_f32_e32 v4, v21, v189
	ds_read2_b32 v[186:187], v6 offset0:92 offset1:124
	s_waitcnt lgkmcnt(5)
	v_fmac_f32_e32 v2, v22, v202
	v_fmac_f32_e32 v4, v23, v203
	v_fmac_f32_e32 v2, v24, v204
	v_fmac_f32_e32 v4, v25, v205
	ds_read2_b32 v[202:203], v154 offset0:172 offset1:240
	s_waitcnt lgkmcnt(5)
	v_fmac_f32_e32 v2, v26, v210
	v_fmac_f32_e32 v4, v27, v211
	v_fmac_f32_e32 v2, v28, v212
	v_fmac_f32_e32 v4, v29, v213
	ds_read_b128 v[210:213], v63 offset:7552
	s_waitcnt lgkmcnt(5)
	v_fmac_f32_e32 v2, v30, v214
	v_fmac_f32_e32 v4, v31, v215
	v_fmac_f32_e32 v2, v32, v216
	v_fmac_f32_e32 v4, v33, v217
	ds_read_b128 v[214:217], v63 offset:7568
	s_waitcnt lgkmcnt(5)
	v_fmac_f32_e32 v2, v34, v190
	v_fmac_f32_e32 v4, v35, v191
	v_fmac_f32_e32 v2, v36, v192
	v_fmac_f32_e32 v4, v37, v193
	ds_read_b128 v[190:193], v63 offset:7584
	s_waitcnt lgkmcnt(5)
	v_fmac_f32_e32 v2, v38, v198
	v_fmac_f32_e32 v4, v39, v199
	v_fmac_f32_e32 v2, v59, v200
	v_fmac_f32_e32 v4, v151, v201
	ds_read_b128 v[198:201], v63 offset:7600
	s_waitcnt lgkmcnt(5)
	v_fmac_f32_e32 v2, v152, v186
	v_add_f32_e32 v2, v4, v2
	s_nop 1
	v_add_f32_dpp v2, v2, v2 quad_perm:[1,0,3,2] row_mask:0xf bank_mask:0xf bound_ctrl:1
	v_fma_f32 v4, v219, v0, -v2
	v_mul_f32_e32 v0, v225, v197
	ds_read_b128 v[194:197], v63 offset:7616
	v_cndmask_b32_e64 v6, v225, v0, s[4:5]
	ds_read_b128 v[222:225], v63 offset:7632
	s_waitcnt lgkmcnt(5)
; __device__ void ph_dnpre(const P& p, float* lds) {
;     ...
;       const int c = tid >> 1, par = tid & 1;
;       float xe[32];
;       float* col = c < 64 ? (B2 + c) : (B1 + c - 64);
;       const float* Lp = B0 + par * 2048;
; #pragma unroll
;       for (int i = 0; i < 64; ++i) {
;         float sc = sBeta[i];
;         if (c >= 64) sc *= sEG[i];
;         const float rhs = col[i * LS] * sc;
;         float a0 = 0.f, a1 = 0.f;
; #pragma unroll
;         for (int jj = 0; 2 * jj + 1 < i; ++jj) {
;           const float l = Lp[i * 32 + jj];
;           if (jj & 1) a1 += l * xe[jj]; else a0 += l * xe[jj];
;         }
;         if (i & 1) {
;           const float l = B0[i * 32 + (i >> 1)];
;           a0 += (par == 0) ? l * xe[i >> 1] : 0.f;
;         }
;         float acc = a0 + a1;
;         acc += dpp_f<DPP_XOR1>(acc);
;         const float xi = rhs - acc;
;         if ((i & 1) == 0) xe[i >> 1] = xi;
;         else xe[i >> 1] = (par == 1) ? xi : xe[i >> 1];
;       }
	v_fma_f32 v7, v14, v210, 0
	v_fma_f32 v9, v15, v211, 0
	v_fmac_f32_e32 v7, v16, v212
	v_fmac_f32_e32 v9, v17, v213
	ds_read_b128 v[210:213], v63 offset:7648
	s_waitcnt lgkmcnt(5)
	v_fmac_f32_e32 v7, v18, v214
	v_fmac_f32_e32 v9, v19, v215
	v_fmac_f32_e32 v7, v20, v216
	v_fmac_f32_e32 v9, v21, v217
	ds_read_b128 v[214:217], v45 offset:52720
	s_waitcnt lgkmcnt(5)
	v_fmac_f32_e32 v7, v22, v190
	v_fmac_f32_e32 v9, v23, v191
	v_fmac_f32_e32 v7, v24, v192
	v_fmac_f32_e32 v9, v25, v193
	ds_read_b128 v[190:193], v45 offset:52976
	s_waitcnt lgkmcnt(5)
	v_fmac_f32_e32 v7, v26, v198
	v_fmac_f32_e32 v9, v27, v199
	v_fmac_f32_e32 v7, v28, v200
	v_fmac_f32_e32 v9, v29, v201
	ds_read_b128 v[198:201], v63 offset:7680
	s_waitcnt lgkmcnt(5)
	v_fmac_f32_e32 v7, v30, v194
	v_fmac_f32_e32 v9, v31, v195
	v_fmac_f32_e32 v7, v32, v196
	v_fmac_f32_e32 v9, v33, v197
	ds_read2_b64 v[194:197], v8 offset0:206 offset1:222
	s_waitcnt lgkmcnt(5)
	v_fmac_f32_e32 v7, v34, v222
	v_fmac_f32_e32 v9, v35, v223
	v_fmac_f32_e32 v7, v36, v224
	v_fmac_f32_e32 v9, v37, v225
	ds_read_b128 v[222:225], v63 offset:7696
	s_waitcnt lgkmcnt(5)
	v_fmac_f32_e32 v7, v38, v210
	v_fmac_f32_e32 v7, v59, v212
	v_mul_f32_e32 v0, v4, v207
	ds_read_b128 v[206:209], v63 offset:7712
	v_fmac_f32_e32 v9, v39, v211
	v_fmac_f32_e32 v7, v152, v187
	v_cndmask_b32_e64 v0, 0, v0, s[6:7]
	v_fmac_f32_e32 v9, v151, v213
	v_add_f32_e32 v0, v7, v0
	v_add_f32_e32 v0, v9, v0
	s_nop 1
	v_add_f32_dpp v0, v0, v0 quad_perm:[1,0,3,2] row_mask:0xf bank_mask:0xf bound_ctrl:1
	v_fma_f32 v0, v202, v6, -v0
	v_cndmask_b32_e64 v12, v0, v4, s[6:7]
	ds_read_b128 v[186:189], v63 offset:7728
	ds_read_b128 v[210:213], v63 offset:7744
	s_waitcnt lgkmcnt(6)
	v_mul_f32_e32 v4, v214, v190
	v_cndmask_b32_e64 v0, v214, v4, s[4:5]
	s_waitcnt lgkmcnt(5)
	v_fma_f32 v4, v14, v198, 0
	v_fma_f32 v158, v15, v199, 0
	v_fmac_f32_e32 v4, v16, v200
	v_fmac_f32_e32 v158, v17, v201
	ds_read_b128 v[198:201], v63 offset:7760
	s_waitcnt lgkmcnt(4)
	v_fmac_f32_e32 v4, v18, v222
	v_fmac_f32_e32 v158, v19, v223
	v_fmac_f32_e32 v4, v20, v224
	v_fmac_f32_e32 v158, v21, v225
	ds_read_b128 v[222:225], v63 offset:7776
	v_add_u32_e32 v218, 0x4000, v62
	ds_read2_b32 v[218:219], v218 offset0:52 offset1:120
	s_waitcnt lgkmcnt(5)
	v_fmac_f32_e32 v4, v22, v206
	v_fmac_f32_e32 v158, v23, v207
	v_fmac_f32_e32 v4, v24, v208
	v_fmac_f32_e32 v158, v25, v209
	ds_read_b128 v[206:209], v63 offset:7808
	s_waitcnt lgkmcnt(5)
	v_fmac_f32_e32 v4, v26, v186
	v_fmac_f32_e32 v158, v27, v187
	v_fmac_f32_e32 v4, v28, v188
	v_fmac_f32_e32 v158, v29, v189
	ds_read2_b32 v[186:187], v153 offset0:190 offset1:255
	s_waitcnt lgkmcnt(5)
	v_fmac_f32_e32 v4, v30, v210
	v_fmac_f32_e32 v158, v31, v211
	v_fmac_f32_e32 v4, v32, v212
	v_fmac_f32_e32 v158, v33, v213
	ds_read_b128 v[210:213], v63 offset:7824
	s_waitcnt lgkmcnt(5)
	v_fmac_f32_e32 v4, v34, v198
	v_fmac_f32_e32 v158, v35, v199
	v_fmac_f32_e32 v4, v36, v200
	v_fmac_f32_e32 v158, v37, v201
	ds_read_b128 v[198:201], v63 offset:7840
	s_waitcnt lgkmcnt(5)
	v_fmac_f32_e32 v4, v38, v222
	v_fmac_f32_e32 v158, v39, v223
	v_fmac_f32_e32 v4, v59, v224
	v_fmac_f32_e32 v158, v151, v225
	ds_read_b128 v[222:225], v63 offset:7856
	v_fmac_f32_e32 v4, v152, v194
	v_fmac_f32_e32 v158, v12, v195
	v_add_f32_e32 v4, v4, v158
	s_nop 1
	v_add_f32_dpp v4, v4, v4 quad_perm:[1,0,3,2] row_mask:0xf bank_mask:0xf bound_ctrl:1
	v_fma_f32 v8, v203, v0, -v4
	v_mul_f32_e32 v0, v215, v191
	v_cndmask_b32_e64 v9, v215, v0, s[4:5]
	ds_read_b128 v[202:205], v63 offset:7872
	s_waitcnt lgkmcnt(5)
	v_fma_f32 v13, v14, v206, 0
	v_fma_f32 v158, v15, v207, 0
	v_fmac_f32_e32 v13, v16, v208
	v_fmac_f32_e32 v158, v17, v209
	ds_read_b128 v[206:209], v63 offset:7888
	s_waitcnt lgkmcnt(5)
	v_mul_f32_e32 v4, v8, v186
	v_cndmask_b32_e64 v4, 0, v4, s[6:7]
	s_waitcnt lgkmcnt(4)
	v_fmac_f32_e32 v13, v18, v210
	v_fmac_f32_e32 v158, v19, v211
	v_fmac_f32_e32 v13, v20, v212
	v_fmac_f32_e32 v158, v21, v213
	ds_read_b128 v[210:213], v63 offset:7904
	s_waitcnt lgkmcnt(4)
	v_fmac_f32_e32 v13, v22, v198
	v_fmac_f32_e32 v158, v23, v199
	v_fmac_f32_e32 v13, v24, v200
	v_fmac_f32_e32 v158, v25, v201
	ds_read_b128 v[198:201], v63 offset:7936
	s_waitcnt lgkmcnt(4)
	v_fmac_f32_e32 v13, v26, v222
	v_fmac_f32_e32 v158, v27, v223
	v_fmac_f32_e32 v13, v28, v224
	v_fmac_f32_e32 v158, v29, v225
	ds_read_b128 v[222:225], v63 offset:7952
	s_waitcnt lgkmcnt(4)
	v_fmac_f32_e32 v13, v30, v202
	v_fmac_f32_e32 v158, v31, v203
	v_fmac_f32_e32 v13, v32, v204
	v_fmac_f32_e32 v158, v33, v205
	ds_read_b128 v[202:205], v63 offset:7968
	s_waitcnt lgkmcnt(4)
	v_fmac_f32_e32 v13, v34, v206
	v_fmac_f32_e32 v158, v35, v207
	v_fmac_f32_e32 v13, v36, v208
	v_fmac_f32_e32 v158, v37, v209
	ds_read_b128 v[206:209], v63 offset:7984
	s_waitcnt lgkmcnt(4)
	v_fmac_f32_e32 v13, v38, v210
	v_fmac_f32_e32 v158, v39, v211
	v_fmac_f32_e32 v13, v59, v212
	v_fmac_f32_e32 v158, v151, v213
	ds_read_b128 v[210:213], v63 offset:8000
	v_fmac_f32_e32 v13, v152, v196
	v_fmac_f32_e32 v158, v12, v197
	ds_read_b128 v[194:197], v63 offset:8016
	v_add_f32_e32 v4, v13, v4
	v_add_f32_e32 v4, v158, v4
	s_nop 1
	v_add_f32_dpp v4, v4, v4 quad_perm:[1,0,3,2] row_mask:0xf bank_mask:0xf bound_ctrl:1
	v_fma_f32 v0, v218, v9, -v4
	v_cndmask_b32_e64 v0, v0, v8, s[6:7]
	v_mul_f32_e32 v4, v216, v192
	v_cndmask_b32_e64 v2, v216, v4, s[4:5]
	s_waitcnt lgkmcnt(5)
	v_fma_f32 v4, v14, v198, 0
	v_fma_f32 v6, v15, v199, 0
	v_fmac_f32_e32 v4, v16, v200
	v_fmac_f32_e32 v6, v17, v201
	ds_read_b128 v[198:201], v63 offset:8032
	s_waitcnt lgkmcnt(5)
	v_fmac_f32_e32 v4, v18, v222
	v_fmac_f32_e32 v6, v19, v223
	v_fmac_f32_e32 v4, v20, v224
	v_fmac_f32_e32 v6, v21, v225
	ds_read_b96 v[222:224], v63 offset:8048
	s_waitcnt lgkmcnt(5)
; __device__ void ph_dnpre(const P& p, float* lds) {
;     ...
;       for (int i = 0; i < 64; ++i) {
;         float sc = sBeta[i];
;         if (c >= 64) sc *= sEG[i];
;         const float rhs = col[i * LS] * sc;
;         float a0 = 0.f, a1 = 0.f;
; #pragma unroll
;         for (int jj = 0; 2 * jj + 1 < i; ++jj) {
;           const float l = Lp[i * 32 + jj];
;           if (jj & 1) a1 += l * xe[jj]; else a0 += l * xe[jj];
;         }
;         if (i & 1) {
;           const float l = B0[i * 32 + (i >> 1)];
;           a0 += (par == 0) ? l * xe[i >> 1] : 0.f;
;         }
;         float acc = a0 + a1;
;         acc += dpp_f<DPP_XOR1>(acc);
;         const float xi = rhs - acc;
;         if ((i & 1) == 0) xe[i >> 1] = xi;
;         else xe[i >> 1] = (par == 1) ? xi : xe[i >> 1];
;       }
; #pragma unroll
;       for (int jj = 0; jj < 32; ++jj) col[(2 * jj + par) * LS] = xe[jj];
;     }
;     __syncthreads();
; #pragma unroll
;     for (int kb = 0; kb < 2; ++kb) {
;       const float4 a = *(const float4*)(B1 + (w * 16 + fr) * LS + kb * 32 + fq * 4);
;       const float4 c = *(const float4*)(B1 + (w * 16 + fr) * LS + kb * 32 + 16 + fq * 4);
;       *(bf16x8*)(DNW + (size_t)chunk * 4096 + ((w * 2 + kb) * 64 + lane) * 8) = pack8(a.x, a.y, a.z, a.w, c.x, c.y, c.z, c.w);
;     }
; #pragma unroll
;     for (int nt = 0; nt < 4; ++nt) {
;       f32x4 u;
; #pragma unroll
;       for (int r = 0; r < 4; ++r) u[r] = B2[(w * 16 + fq * 4 + r) * LS + nt * 16 + fr];
;       *(f32x4*)(Ubuf + (size_t)chunk * 4096 + ((w * 4 + nt) * 64 + lane) * 4) = u;
;     }
;     if (tid == 0) p_gl[chunk] = __expf(glast);
	v_fmac_f32_e32 v4, v22, v202
	v_fmac_f32_e32 v6, v23, v203
	v_fmac_f32_e32 v4, v24, v204
	v_fmac_f32_e32 v6, v25, v205
	ds_read_b32 v202, v62 offset:17136
	s_waitcnt lgkmcnt(5)
	v_fmac_f32_e32 v4, v26, v206
	v_fmac_f32_e32 v6, v27, v207
	v_fmac_f32_e32 v4, v28, v208
	v_fmac_f32_e32 v6, v29, v209
	ds_read_b128 v[206:209], v63 offset:8064
	s_waitcnt lgkmcnt(5)
	v_fmac_f32_e32 v4, v30, v210
	v_fmac_f32_e32 v6, v31, v211
	v_fmac_f32_e32 v4, v32, v212
	v_fmac_f32_e32 v6, v33, v213
	ds_read_b96 v[210:212], v63 offset:8176
	s_waitcnt lgkmcnt(5)
	v_fmac_f32_e32 v4, v34, v194
	v_fmac_f32_e32 v6, v35, v195
	v_fmac_f32_e32 v4, v36, v196
	v_fmac_f32_e32 v6, v37, v197
	ds_read_b128 v[194:197], v63 offset:8080
	s_waitcnt lgkmcnt(5)
	v_fmac_f32_e32 v4, v38, v198
	v_fmac_f32_e32 v6, v39, v199
	v_fmac_f32_e32 v4, v59, v200
	v_fmac_f32_e32 v6, v151, v201
	ds_read_b128 v[198:201], v63 offset:8096
	s_waitcnt lgkmcnt(5)
	v_fmac_f32_e32 v4, v152, v222
	v_fmac_f32_e32 v6, v12, v223
	v_fmac_f32_e32 v4, v0, v224
	ds_read_b128 v[222:225], v63 offset:8112
	v_add_f32_e32 v4, v6, v4
	s_nop 1
	v_add_f32_dpp v4, v4, v4 quad_perm:[1,0,3,2] row_mask:0xf bank_mask:0xf bound_ctrl:1
	v_fma_f32 v1, v219, v2, -v4
	v_mul_f32_e32 v2, v217, v193
	ds_read_b128 v[190:193], v63 offset:8128
	v_cndmask_b32_e64 v10, v217, v2, s[4:5]
	ds_read_b128 v[214:217], v63 offset:8144
	s_waitcnt lgkmcnt(6)
	v_fma_f32 v13, v14, v206, 0
	v_fma_f32 v153, v15, v207, 0
	v_fmac_f32_e32 v13, v16, v208
	v_fmac_f32_e32 v153, v17, v209
	ds_read_b128 v[206:209], v63 offset:8160
	s_waitcnt lgkmcnt(5)
	v_fmac_f32_e32 v13, v18, v194
	v_fmac_f32_e32 v153, v19, v195
	v_fmac_f32_e32 v13, v20, v196
	v_fmac_f32_e32 v153, v21, v197
	s_waitcnt lgkmcnt(4)
	v_fmac_f32_e32 v13, v22, v198
	v_fmac_f32_e32 v153, v23, v199
	v_fmac_f32_e32 v13, v24, v200
	v_fmac_f32_e32 v153, v25, v201
	s_waitcnt lgkmcnt(3)
	v_fmac_f32_e32 v13, v26, v222
	v_fmac_f32_e32 v153, v27, v223
	v_fmac_f32_e32 v13, v28, v224
	v_fmac_f32_e32 v153, v29, v225
	s_waitcnt lgkmcnt(2)
	v_fmac_f32_e32 v13, v30, v190
	v_fmac_f32_e32 v153, v31, v191
	v_fmac_f32_e32 v13, v32, v192
	v_fmac_f32_e32 v153, v33, v193
	s_waitcnt lgkmcnt(1)
	v_fmac_f32_e32 v13, v34, v214
	v_fmac_f32_e32 v153, v35, v215
	v_fmac_f32_e32 v13, v36, v216
	v_fmac_f32_e32 v153, v37, v217
	ds_write2_b32 v90, v14, v15 offset1:136
	v_add_u32_e32 v14, 0x8800, v91
	s_waitcnt lgkmcnt(1)
	v_fmac_f32_e32 v13, v38, v206
	v_fmac_f32_e32 v13, v59, v208
	v_fmac_f32_e32 v153, v39, v207
	v_fmac_f32_e32 v13, v152, v210
	v_mul_f32_e32 v2, v1, v187
	v_fmac_f32_e32 v153, v151, v209
	v_fmac_f32_e32 v13, v0, v212
	v_cndmask_b32_e64 v2, 0, v2, s[6:7]
	v_fmac_f32_e32 v153, v12, v211
	v_add_f32_e32 v2, v13, v2
	v_add_f32_e32 v2, v153, v2
	v_lshl_add_u64 v[8:9], v[50:51], 0, s[56:57]
	s_nop 0
	v_add_f32_dpp v2, v2, v2 quad_perm:[1,0,3,2] row_mask:0xf bank_mask:0xf bound_ctrl:1
	v_fma_f32 v2, v202, v10, -v2
	v_cndmask_b32_e64 v1, v2, v1, s[6:7]
	v_add_u32_e32 v2, 0x400, v90
	ds_write2_b32 v2, v16, v17 offset0:16 offset1:152
	v_add_u32_e32 v2, 0x800, v90
	ds_write2_b32 v2, v18, v19 offset0:32 offset1:168
	v_add_u32_e32 v2, 0xc00, v90
	ds_write2_b32 v2, v20, v21 offset0:48 offset1:184
	v_add_u32_e32 v2, 0x1000, v90
	ds_write2_b32 v2, v22, v23 offset0:64 offset1:200
	v_add_u32_e32 v2, 0x1400, v90
	ds_write2_b32 v2, v24, v25 offset0:80 offset1:216
	v_add_u32_e32 v2, 0x1800, v90
	ds_write2_b32 v2, v26, v27 offset0:96 offset1:232
	v_add_u32_e32 v2, 0x1c00, v90
	ds_write2_b32 v2, v28, v29 offset0:112 offset1:248
	v_add_u32_e32 v2, 0x2200, v90
	ds_write2_b32 v2, v30, v31 offset1:136
	v_add_u32_e32 v2, 0x2600, v90
	ds_write2_b32 v2, v32, v33 offset0:16 offset1:152
	v_add_u32_e32 v2, 0x2a00, v90
	ds_write2_b32 v2, v34, v35 offset0:32 offset1:168
	v_add_u32_e32 v2, 0x2e00, v90
	ds_write2_b32 v2, v36, v37 offset0:48 offset1:184
	v_add_u32_e32 v2, 0x3200, v90
	ds_write2_b32 v2, v38, v39 offset0:64 offset1:200
	v_add_u32_e32 v2, 0x3600, v90
	ds_write2_b32 v2, v59, v151 offset0:80 offset1:216
	v_add_u32_e32 v2, 0x3a00, v90
	ds_write2_b32 v2, v152, v12 offset0:96 offset1:232
	v_add_u32_e32 v2, 0x3e00, v90
	ds_write2_b32 v2, v0, v1 offset0:112 offset1:248
	s_waitcnt lgkmcnt(0)
	s_barrier
	ds_read_b128 v[0:3], v68 offset:17408
	ds_read_b128 v[4:7], v68 offset:17472
	v_lshl_add_u64 v[12:13], v[48:49], 0, s[10:11]
	s_waitcnt lgkmcnt(1)
	v_cvt_pk_bf16_f32 v0, v0, v1
	v_cvt_pk_bf16_f32 v1, v2, v3
	s_waitcnt lgkmcnt(0)
	v_cvt_pk_bf16_f32 v2, v4, v5
	v_cvt_pk_bf16_f32 v3, v6, v7
	global_store_dwordx4 v[8:9], v[0:3], off
	ds_read_b128 v[0:3], v68 offset:17536
	ds_read_b128 v[4:7], v68 offset:17600
	s_waitcnt lgkmcnt(1)
	v_cvt_pk_bf16_f32 v0, v0, v1
	v_cvt_pk_bf16_f32 v1, v2, v3
	s_waitcnt lgkmcnt(0)
	v_cvt_pk_bf16_f32 v2, v4, v5
	v_cvt_pk_bf16_f32 v3, v6, v7
	global_store_dwordx4 v[8:9], v[0:3], off offset:1024
	ds_read2_b32 v[8:9], v14 offset1:16
	ds_read2_b32 v[0:1], v14 offset0:68 offset1:84
	ds_read2_b32 v[10:11], v14 offset0:136 offset1:152
	ds_read2_b32 v[2:3], v14 offset0:204 offset1:220
	s_waitcnt lgkmcnt(3)
	v_mov_b32_e32 v4, v8
	s_waitcnt lgkmcnt(2)
	v_mov_b32_e32 v5, v0
	s_waitcnt lgkmcnt(1)
	v_mov_b32_e32 v6, v10
	s_waitcnt lgkmcnt(0)
	v_mov_b32_e32 v7, v2
	v_mov_b32_e32 v0, v9
	v_mov_b32_e32 v2, v11
	global_store_dwordx4 v[12:13], v[4:7], off
	global_store_dwordx4 v[12:13], v[0:3], off offset:1024
	ds_read2_b32 v[8:9], v14 offset0:32 offset1:48
	ds_read2_b32 v[0:1], v14 offset0:100 offset1:116
	ds_read2_b32 v[10:11], v14 offset0:168 offset1:184
	ds_read2_b32 v[2:3], v14 offset0:236 offset1:252
	s_waitcnt lgkmcnt(3)
	v_mov_b32_e32 v4, v8
	s_waitcnt lgkmcnt(2)
	v_mov_b32_e32 v5, v0
	s_waitcnt lgkmcnt(1)
	v_mov_b32_e32 v6, v10
	s_waitcnt lgkmcnt(0)
	v_mov_b32_e32 v7, v2
	v_mov_b32_e32 v0, v9
	v_mov_b32_e32 v2, v11
	global_store_dwordx4 v[12:13], v[4:7], off offset:2048
	global_store_dwordx4 v[12:13], v[0:3], off offset:3072
	s_and_saveexec_b64 s[10:11], s[8:9]
	s_cbranch_execz .LBB0_159
	v_mul_f32_e32 v0, 0x3fb8aa3b, v44
	v_exp_f32_e32 v0, v0
	s_lshl_b64 s[2:3], s[2:3], 2
	s_add_u32 s2, s75, s2
	s_addc_u32 s3, s33, s3
	global_store_dword v45, v0, s[2:3]
	s_branch .LBB0_159
